# layer-1 V^T epilogue rewritten for all three dilation groups (lane transpositions by DPP+v_perm, 8/16-byte stores)
# speedup vs baseline: 1.0415x; 1.0079x over previous
.Lvt_n2_P9:
	s_cmp_lg_u32 s2, 2
	s_cbranch_scc1 .Lvt_n1_P9
	v_lshl_add_u64 v[160:161], v[194:195], 3, s[10:11]
	global_load_dwordx2 v[162:163], v[160:161], off offset:128
	global_load_dwordx2 v[208:209], v[160:161], off offset:256
	global_load_dwordx2 v[210:211], v[160:161], off offset:384
	global_load_dwordx2 v[200:201], v[160:161], off offset:1024
	global_load_dwordx2 v[252:253], v[160:161], off offset:1152
	global_load_dwordx2 v[254:255], v[160:161], off offset:1280
	global_load_dwordx2 v[248:249], v[160:161], off offset:1408
	s_waitcnt vmcnt(0)
	v_mul_f32_e32 v193, 0x3a800000, v196
	v_mul_f32_e32 v176, v193, v193
	v_fma_f32 v176, v197, s40, -v176
	v_add_f32_e32 v176, 0x3727c5ac, v176
	v_rsq_f32_e32 v195, v176
	v_fma_f32 v156, -v104, v193, v156
	v_fma_f32 v157, -v105, v193, v157
	v_fma_f32 v158, -v106, v193, v158
	v_fma_f32 v159, -v107, v193, v159
	v_fma_f32 v152, -v96, v193, v152
	v_fma_f32 v153, -v97, v193, v153
	v_fma_f32 v154, -v98, v193, v154
	v_fma_f32 v155, -v99, v193, v155
	v_fma_f32 v148, -v112, v193, v148
	v_fma_f32 v149, -v113, v193, v149
	v_fma_f32 v150, -v114, v193, v150
	v_fma_f32 v151, -v115, v193, v151
	v_fma_f32 v144, -v124, v193, v144
	v_fma_f32 v145, -v125, v193, v145
	v_fma_f32 v146, -v126, v193, v146
	v_fma_f32 v147, -v127, v193, v147
	v_fma_f32 v156, v156, v195, v108
	v_fma_f32 v157, v157, v195, v109
	v_fma_f32 v158, v158, v195, v110
	v_fma_f32 v159, v159, v195, v111
	v_fma_f32 v152, v152, v195, v100
	v_fma_f32 v153, v153, v195, v101
	v_fma_f32 v154, v154, v195, v102
	v_fma_f32 v155, v155, v195, v103
	v_fma_f32 v148, v148, v195, v116
	v_fma_f32 v149, v149, v195, v117
	v_fma_f32 v150, v150, v195, v118
	v_fma_f32 v151, v151, v195, v119
	v_fma_f32 v144, v144, v195, v120
	v_fma_f32 v145, v145, v195, v121
	v_fma_f32 v146, v146, v195, v122
	v_fma_f32 v147, v147, v195, v123
	v_mul_f32_e32 v193, 0x3a800000, v162
	v_mul_f32_e32 v176, v193, v193
	v_fma_f32 v176, v163, s40, -v176
	v_add_f32_e32 v176, 0x3727c5ac, v176
	v_rsq_f32_e32 v195, v176
	v_fma_f32 v140, -v104, v193, v140
	v_fma_f32 v141, -v105, v193, v141
	v_fma_f32 v142, -v106, v193, v142
	v_fma_f32 v143, -v107, v193, v143
	v_fma_f32 v136, -v96, v193, v136
	v_fma_f32 v137, -v97, v193, v137
	v_fma_f32 v138, -v98, v193, v138
	v_fma_f32 v139, -v99, v193, v139
	v_fma_f32 v132, -v112, v193, v132
	v_fma_f32 v133, -v113, v193, v133
	v_fma_f32 v134, -v114, v193, v134
	v_fma_f32 v135, -v115, v193, v135
	v_fma_f32 v128, -v124, v193, v128
	v_fma_f32 v129, -v125, v193, v129
	v_fma_f32 v130, -v126, v193, v130
	v_fma_f32 v131, -v127, v193, v131
	v_fma_f32 v140, v140, v195, v108
	v_fma_f32 v141, v141, v195, v109
	v_fma_f32 v142, v142, v195, v110
	v_fma_f32 v143, v143, v195, v111
	v_fma_f32 v136, v136, v195, v100
	v_fma_f32 v137, v137, v195, v101
	v_fma_f32 v138, v138, v195, v102
	v_fma_f32 v139, v139, v195, v103
	v_fma_f32 v132, v132, v195, v116
	v_fma_f32 v133, v133, v195, v117
	v_fma_f32 v134, v134, v195, v118
	v_fma_f32 v135, v135, v195, v119
	v_fma_f32 v128, v128, v195, v120
	v_fma_f32 v129, v129, v195, v121
	v_fma_f32 v130, v130, v195, v122
	v_fma_f32 v131, v131, v195, v123
	v_mul_f32_e32 v193, 0x3a800000, v208
	v_mul_f32_e32 v176, v193, v193
	v_fma_f32 v176, v209, s40, -v176
	v_add_f32_e32 v176, 0x3727c5ac, v176
	v_rsq_f32_e32 v195, v176
	v_fma_f32 v92, -v104, v193, v92
	v_fma_f32 v93, -v105, v193, v93
	v_fma_f32 v94, -v106, v193, v94
	v_fma_f32 v95, -v107, v193, v95
	v_fma_f32 v88, -v96, v193, v88
	v_fma_f32 v89, -v97, v193, v89
	v_fma_f32 v90, -v98, v193, v90
	v_fma_f32 v91, -v99, v193, v91
	v_fma_f32 v84, -v112, v193, v84
	v_fma_f32 v85, -v113, v193, v85
	v_fma_f32 v86, -v114, v193, v86
	v_fma_f32 v87, -v115, v193, v87
	v_fma_f32 v80, -v124, v193, v80
	v_fma_f32 v81, -v125, v193, v81
	v_fma_f32 v82, -v126, v193, v82
	v_fma_f32 v83, -v127, v193, v83
	v_fma_f32 v92, v92, v195, v108
	v_fma_f32 v93, v93, v195, v109
	v_fma_f32 v94, v94, v195, v110
	v_fma_f32 v95, v95, v195, v111
	v_fma_f32 v88, v88, v195, v100
	v_fma_f32 v89, v89, v195, v101
	v_fma_f32 v90, v90, v195, v102
	v_fma_f32 v91, v91, v195, v103
	v_fma_f32 v84, v84, v195, v116
	v_fma_f32 v85, v85, v195, v117
	v_fma_f32 v86, v86, v195, v118
	v_fma_f32 v87, v87, v195, v119
	v_fma_f32 v80, v80, v195, v120
	v_fma_f32 v81, v81, v195, v121
	v_fma_f32 v82, v82, v195, v122
	v_fma_f32 v83, v83, v195, v123
	v_mul_f32_e32 v193, 0x3a800000, v210
	v_mul_f32_e32 v176, v193, v193
	v_fma_f32 v176, v211, s40, -v176
	v_add_f32_e32 v176, 0x3727c5ac, v176
	v_rsq_f32_e32 v195, v176
	v_fma_f32 v76, -v104, v193, v76
	v_fma_f32 v77, -v105, v193, v77
	v_fma_f32 v78, -v106, v193, v78
	v_fma_f32 v79, -v107, v193, v79
	v_fma_f32 v72, -v96, v193, v72
	v_fma_f32 v73, -v97, v193, v73
	v_fma_f32 v74, -v98, v193, v74
	v_fma_f32 v75, -v99, v193, v75
	v_fma_f32 v68, -v112, v193, v68
	v_fma_f32 v69, -v113, v193, v69
	v_fma_f32 v70, -v114, v193, v70
	v_fma_f32 v71, -v115, v193, v71
	v_fma_f32 v64, -v124, v193, v64
	v_fma_f32 v65, -v125, v193, v65
	v_fma_f32 v66, -v126, v193, v66
	v_fma_f32 v67, -v127, v193, v67
	v_fma_f32 v76, v76, v195, v108
	v_fma_f32 v77, v77, v195, v109
	v_fma_f32 v78, v78, v195, v110
	v_fma_f32 v79, v79, v195, v111
	v_fma_f32 v72, v72, v195, v100
	v_fma_f32 v73, v73, v195, v101
	v_fma_f32 v74, v74, v195, v102
	v_fma_f32 v75, v75, v195, v103
	v_fma_f32 v68, v68, v195, v116
	v_fma_f32 v69, v69, v195, v117
	v_fma_f32 v70, v70, v195, v118
	v_fma_f32 v71, v71, v195, v119
	v_fma_f32 v64, v64, v195, v120
	v_fma_f32 v65, v65, v195, v121
	v_fma_f32 v66, v66, v195, v122
	v_fma_f32 v67, v67, v195, v123
	v_mul_f32_e32 v193, 0x3a800000, v200
	v_mul_f32_e32 v176, v193, v193
	v_fma_f32 v176, v201, s40, -v176
	v_add_f32_e32 v176, 0x3727c5ac, v176
	v_rsq_f32_e32 v195, v176
	v_fma_f32 v60, -v104, v193, v60
	v_fma_f32 v61, -v105, v193, v61
	v_fma_f32 v62, -v106, v193, v62
	v_fma_f32 v63, -v107, v193, v63
	v_fma_f32 v56, -v96, v193, v56
	v_fma_f32 v57, -v97, v193, v57
	v_fma_f32 v58, -v98, v193, v58
	v_fma_f32 v59, -v99, v193, v59
	v_fma_f32 v52, -v112, v193, v52
	v_fma_f32 v53, -v113, v193, v53
	v_fma_f32 v54, -v114, v193, v54
	v_fma_f32 v55, -v115, v193, v55
	v_fma_f32 v48, -v124, v193, v48
	v_fma_f32 v49, -v125, v193, v49
	v_fma_f32 v50, -v126, v193, v50
	v_fma_f32 v51, -v127, v193, v51
	v_fma_f32 v60, v60, v195, v108
	v_fma_f32 v61, v61, v195, v109
	v_fma_f32 v62, v62, v195, v110
	v_fma_f32 v63, v63, v195, v111
	v_fma_f32 v56, v56, v195, v100
	v_fma_f32 v57, v57, v195, v101
	v_fma_f32 v58, v58, v195, v102
	v_fma_f32 v59, v59, v195, v103
	v_fma_f32 v52, v52, v195, v116
	v_fma_f32 v53, v53, v195, v117
	v_fma_f32 v54, v54, v195, v118
	v_fma_f32 v55, v55, v195, v119
	v_fma_f32 v48, v48, v195, v120
	v_fma_f32 v49, v49, v195, v121
	v_fma_f32 v50, v50, v195, v122
	v_fma_f32 v51, v51, v195, v123
	v_mul_f32_e32 v193, 0x3a800000, v252
	v_mul_f32_e32 v176, v193, v193
	v_fma_f32 v176, v253, s40, -v176
	v_add_f32_e32 v176, 0x3727c5ac, v176
	v_rsq_f32_e32 v195, v176
	v_fma_f32 v44, -v104, v193, v44
	v_fma_f32 v45, -v105, v193, v45
	v_fma_f32 v46, -v106, v193, v46
	v_fma_f32 v47, -v107, v193, v47
	v_fma_f32 v40, -v96, v193, v40
	v_fma_f32 v41, -v97, v193, v41
	v_fma_f32 v42, -v98, v193, v42
	v_fma_f32 v43, -v99, v193, v43
	v_fma_f32 v36, -v112, v193, v36
	v_fma_f32 v37, -v113, v193, v37
	v_fma_f32 v38, -v114, v193, v38
	v_fma_f32 v39, -v115, v193, v39
	v_fma_f32 v32, -v124, v193, v32
	v_fma_f32 v33, -v125, v193, v33
	v_fma_f32 v34, -v126, v193, v34
	v_fma_f32 v35, -v127, v193, v35
	v_fma_f32 v44, v44, v195, v108
	v_fma_f32 v45, v45, v195, v109
	v_fma_f32 v46, v46, v195, v110
	v_fma_f32 v47, v47, v195, v111
	v_fma_f32 v40, v40, v195, v100
	v_fma_f32 v41, v41, v195, v101
	v_fma_f32 v42, v42, v195, v102
	v_fma_f32 v43, v43, v195, v103
	v_fma_f32 v36, v36, v195, v116
	v_fma_f32 v37, v37, v195, v117
	v_fma_f32 v38, v38, v195, v118
	v_fma_f32 v39, v39, v195, v119
	v_fma_f32 v32, v32, v195, v120
	v_fma_f32 v33, v33, v195, v121
	v_fma_f32 v34, v34, v195, v122
	v_fma_f32 v35, v35, v195, v123
	v_mul_f32_e32 v193, 0x3a800000, v254
	v_mul_f32_e32 v176, v193, v193
	v_fma_f32 v176, v255, s40, -v176
	v_add_f32_e32 v176, 0x3727c5ac, v176
	v_rsq_f32_e32 v195, v176
	v_fma_f32 v28, -v104, v193, v28
	v_fma_f32 v29, -v105, v193, v29
	v_fma_f32 v30, -v106, v193, v30
	v_fma_f32 v31, -v107, v193, v31
	v_fma_f32 v24, -v96, v193, v24
	v_fma_f32 v25, -v97, v193, v25
	v_fma_f32 v26, -v98, v193, v26
	v_fma_f32 v27, -v99, v193, v27
	v_fma_f32 v20, -v112, v193, v20
	v_fma_f32 v21, -v113, v193, v21
	v_fma_f32 v22, -v114, v193, v22
	v_fma_f32 v23, -v115, v193, v23
	v_fma_f32 v16, -v124, v193, v16
	v_fma_f32 v17, -v125, v193, v17
	v_fma_f32 v18, -v126, v193, v18
	v_fma_f32 v19, -v127, v193, v19
	v_fma_f32 v28, v28, v195, v108
	v_fma_f32 v29, v29, v195, v109
	v_fma_f32 v30, v30, v195, v110
	v_fma_f32 v31, v31, v195, v111
	v_fma_f32 v24, v24, v195, v100
	v_fma_f32 v25, v25, v195, v101
	v_fma_f32 v26, v26, v195, v102
	v_fma_f32 v27, v27, v195, v103
	v_fma_f32 v20, v20, v195, v116
	v_fma_f32 v21, v21, v195, v117
	v_fma_f32 v22, v22, v195, v118
	v_fma_f32 v23, v23, v195, v119
	v_fma_f32 v16, v16, v195, v120
	v_fma_f32 v17, v17, v195, v121
	v_fma_f32 v18, v18, v195, v122
	v_fma_f32 v19, v19, v195, v123
	v_mul_f32_e32 v193, 0x3a800000, v248
	v_mul_f32_e32 v176, v193, v193
	v_fma_f32 v176, v249, s40, -v176
	v_add_f32_e32 v176, 0x3727c5ac, v176
	v_rsq_f32_e32 v195, v176
	v_fma_f32 v12, -v104, v193, v12
	v_fma_f32 v13, -v105, v193, v13
	v_fma_f32 v14, -v106, v193, v14
	v_fma_f32 v15, -v107, v193, v15
	v_fma_f32 v8, -v96, v193, v8
	v_fma_f32 v9, -v97, v193, v9
	v_fma_f32 v10, -v98, v193, v10
	v_fma_f32 v11, -v99, v193, v11
	v_fma_f32 v4, -v112, v193, v4
	v_fma_f32 v5, -v113, v193, v5
	v_fma_f32 v6, -v114, v193, v6
	v_fma_f32 v7, -v115, v193, v7
	v_fma_f32 v0, -v124, v193, v0
	v_fma_f32 v1, -v125, v193, v1
	v_fma_f32 v2, -v126, v193, v2
	v_fma_f32 v3, -v127, v193, v3
	v_fma_f32 v12, v12, v195, v108
	v_fma_f32 v13, v13, v195, v109
	v_fma_f32 v14, v14, v195, v110
	v_fma_f32 v15, v15, v195, v111
	v_fma_f32 v8, v8, v195, v100
	v_fma_f32 v9, v9, v195, v101
	v_fma_f32 v10, v10, v195, v102
	v_fma_f32 v11, v11, v195, v103
	v_fma_f32 v4, v4, v195, v116
	v_fma_f32 v5, v5, v195, v117
	v_fma_f32 v6, v6, v195, v118
	v_fma_f32 v7, v7, v195, v119
	v_fma_f32 v0, v0, v195, v120
	v_fma_f32 v1, v1, v195, v121
	v_fma_f32 v2, v2, v195, v122
	v_fma_f32 v3, v3, v195, v123
	s_sub_i32 s45, 13, s2
	v_and_b32_e32 v162, 0x1fcf, v194
	v_lshlrev_b32_e32 v160, s45, v194
	v_and_b32_e32 v163, 0x1ffe, v160
	v_lshrrev_b32_e32 v176, s2, v162
	v_or_b32_e32 v193, v163, v176
	v_bitop3_b32 v163, v163, s72, v176 bitop3:0xc8
	v_lshlrev_b32_e32 v176, 1, v193
	v_lshrrev_b32_e32 v193, 1, v193
	v_and_b32_e32 v176, 8, v176
	v_and_b32_e32 v193, 4, v193
	v_or3_b32 v163, v176, v163, v193
	s_ashr_i32 s0, s3, 13
	s_mul_i32 s0, s0, 12
	s_add_i32 s0, s0, s43
	s_ashr_i32 s1, s0, 31
	s_lshl_b64 s[0:1], s[0:1], 20
	v_lshl_add_u64 v[160:161], v[182:183], 0, s[0:1]
	v_lshlrev_b32_e32 v176, 1, v163
	v_lshl_add_u64 v[200:201], v[160:161], 0, v[176:177]
	v_mbcnt_lo_u32_b32 v247, -1, 0
	v_mbcnt_hi_u32_b32 v247, -1, v247
	v_lshrrev_b32_e32 v176, 2, v247
	v_and_b32_e32 v176, 3, v176
	v_mul_u32_u24_e32 v176, 0x3ffe, v176
	v_add_co_u32_e32 v200, vcc, v200, v176
	s_nop 1
	v_addc_co_u32_e32 v201, vcc, 0, v201, vcc
	v_add_co_u32_e32 v160, vcc, s59, v200
	s_nop 1
	v_addc_co_u32_e32 v161, vcc, 0, v201, vcc
	v_add_co_u32_e32 v162, vcc, s74, v200
	s_nop 1
	v_addc_co_u32_e32 v163, vcc, 0, v201, vcc
	v_add_co_u32_e32 v208, vcc, s78, v200
	s_nop 1
	v_addc_co_u32_e32 v209, vcc, 0, v201, vcc
	v_and_b32_e32 v176, 4, v247
	v_mov_b32_e32 v193, 0x5040100
	v_mov_b32_e32 v195, 0x3020706
	v_cmp_ne_u32_e32 vcc, 0, v176
	v_and_b32_e32 v176, 8, v247
	s_nop 1
	v_cndmask_b32_e32 v193, v193, v195, vcc
	v_cmp_ne_u32_e32 vcc, 0, v176
	s_nop 1
	v_cvt_pk_bf16_f32 v96, v156, v157
	v_cvt_pk_bf16_f32 v98, v158, v159
	v_cvt_pk_bf16_f32 v100, v152, v153
	v_cvt_pk_bf16_f32 v102, v154, v155
	v_cvt_pk_bf16_f32 v104, v148, v149
	v_cvt_pk_bf16_f32 v106, v150, v151
	v_cvt_pk_bf16_f32 v108, v144, v145
	v_cvt_pk_bf16_f32 v110, v146, v147
	v_mov_b32_dpp v97, v96 row_shl:4 row_mask:0xf bank_mask:0x5
	v_mov_b32_dpp v99, v98 row_shl:4 row_mask:0xf bank_mask:0x5
	v_mov_b32_dpp v101, v100 row_shl:4 row_mask:0xf bank_mask:0x5
	v_mov_b32_dpp v103, v102 row_shl:4 row_mask:0xf bank_mask:0x5
	v_mov_b32_dpp v105, v104 row_shl:4 row_mask:0xf bank_mask:0x5
	v_mov_b32_dpp v107, v106 row_shl:4 row_mask:0xf bank_mask:0x5
	v_mov_b32_dpp v109, v108 row_shl:4 row_mask:0xf bank_mask:0x5
	v_mov_b32_dpp v111, v110 row_shl:4 row_mask:0xf bank_mask:0x5
	v_mov_b32_dpp v97, v96 row_shr:4 row_mask:0xf bank_mask:0xa
	v_mov_b32_dpp v99, v98 row_shr:4 row_mask:0xf bank_mask:0xa
	v_mov_b32_dpp v101, v100 row_shr:4 row_mask:0xf bank_mask:0xa
	v_mov_b32_dpp v103, v102 row_shr:4 row_mask:0xf bank_mask:0xa
	v_mov_b32_dpp v105, v104 row_shr:4 row_mask:0xf bank_mask:0xa
	v_mov_b32_dpp v107, v106 row_shr:4 row_mask:0xf bank_mask:0xa
	v_mov_b32_dpp v109, v108 row_shr:4 row_mask:0xf bank_mask:0xa
	v_mov_b32_dpp v111, v110 row_shr:4 row_mask:0xf bank_mask:0xa
	v_perm_b32 v96, v97, v96, v193
	v_perm_b32 v98, v99, v98, v193
	v_perm_b32 v100, v101, v100, v193
	v_perm_b32 v102, v103, v102, v193
	v_perm_b32 v104, v105, v104, v193
	v_perm_b32 v106, v107, v106, v193
	v_perm_b32 v108, v109, v108, v193
	v_perm_b32 v110, v111, v110, v193
	v_mov_b32_dpp v97, v96 row_ror:8 row_mask:0xf bank_mask:0xf
	v_mov_b32_dpp v99, v98 row_ror:8 row_mask:0xf bank_mask:0xf
	v_mov_b32_dpp v101, v100 row_ror:8 row_mask:0xf bank_mask:0xf
	v_mov_b32_dpp v103, v102 row_ror:8 row_mask:0xf bank_mask:0xf
	v_mov_b32_dpp v105, v104 row_ror:8 row_mask:0xf bank_mask:0xf
	v_mov_b32_dpp v107, v106 row_ror:8 row_mask:0xf bank_mask:0xf
	v_mov_b32_dpp v109, v108 row_ror:8 row_mask:0xf bank_mask:0xf
	v_mov_b32_dpp v111, v110 row_ror:8 row_mask:0xf bank_mask:0xf
	v_cndmask_b32_e32 v96, v96, v99, vcc
	v_cndmask_b32_e32 v97, v97, v98, vcc
	v_cndmask_b32_e32 v100, v100, v103, vcc
	v_cndmask_b32_e32 v101, v101, v102, vcc
	v_cndmask_b32_e32 v104, v104, v107, vcc
	v_cndmask_b32_e32 v105, v105, v106, vcc
	v_cndmask_b32_e32 v108, v108, v111, vcc
	v_cndmask_b32_e32 v109, v109, v110, vcc
	v_cvt_pk_bf16_f32 v112, v92, v93
	v_cvt_pk_bf16_f32 v114, v94, v95
	v_cvt_pk_bf16_f32 v116, v88, v89
	v_cvt_pk_bf16_f32 v118, v90, v91
	v_cvt_pk_bf16_f32 v120, v84, v85
	v_cvt_pk_bf16_f32 v122, v86, v87
	v_cvt_pk_bf16_f32 v124, v80, v81
	v_cvt_pk_bf16_f32 v126, v82, v83
	v_mov_b32_dpp v113, v112 row_shl:4 row_mask:0xf bank_mask:0x5
	v_mov_b32_dpp v115, v114 row_shl:4 row_mask:0xf bank_mask:0x5
	v_mov_b32_dpp v117, v116 row_shl:4 row_mask:0xf bank_mask:0x5
	v_mov_b32_dpp v119, v118 row_shl:4 row_mask:0xf bank_mask:0x5
	v_mov_b32_dpp v121, v120 row_shl:4 row_mask:0xf bank_mask:0x5
	v_mov_b32_dpp v123, v122 row_shl:4 row_mask:0xf bank_mask:0x5
	v_mov_b32_dpp v125, v124 row_shl:4 row_mask:0xf bank_mask:0x5
	v_mov_b32_dpp v127, v126 row_shl:4 row_mask:0xf bank_mask:0x5
	v_mov_b32_dpp v113, v112 row_shr:4 row_mask:0xf bank_mask:0xa
	v_mov_b32_dpp v115, v114 row_shr:4 row_mask:0xf bank_mask:0xa
	v_mov_b32_dpp v117, v116 row_shr:4 row_mask:0xf bank_mask:0xa
	v_mov_b32_dpp v119, v118 row_shr:4 row_mask:0xf bank_mask:0xa
	v_mov_b32_dpp v121, v120 row_shr:4 row_mask:0xf bank_mask:0xa
	v_mov_b32_dpp v123, v122 row_shr:4 row_mask:0xf bank_mask:0xa
	v_mov_b32_dpp v125, v124 row_shr:4 row_mask:0xf bank_mask:0xa
	v_mov_b32_dpp v127, v126 row_shr:4 row_mask:0xf bank_mask:0xa
	v_perm_b32 v112, v113, v112, v193
	v_perm_b32 v114, v115, v114, v193
	v_perm_b32 v116, v117, v116, v193
	v_perm_b32 v118, v119, v118, v193
	v_perm_b32 v120, v121, v120, v193
	v_perm_b32 v122, v123, v122, v193
	v_perm_b32 v124, v125, v124, v193
	v_perm_b32 v126, v127, v126, v193
	v_mov_b32_dpp v113, v112 row_ror:8 row_mask:0xf bank_mask:0xf
	v_mov_b32_dpp v115, v114 row_ror:8 row_mask:0xf bank_mask:0xf
	v_mov_b32_dpp v117, v116 row_ror:8 row_mask:0xf bank_mask:0xf
	v_mov_b32_dpp v119, v118 row_ror:8 row_mask:0xf bank_mask:0xf
	v_mov_b32_dpp v121, v120 row_ror:8 row_mask:0xf bank_mask:0xf
	v_mov_b32_dpp v123, v122 row_ror:8 row_mask:0xf bank_mask:0xf
	v_mov_b32_dpp v125, v124 row_ror:8 row_mask:0xf bank_mask:0xf
	v_mov_b32_dpp v127, v126 row_ror:8 row_mask:0xf bank_mask:0xf
	v_cndmask_b32_e32 v112, v112, v115, vcc
	v_cndmask_b32_e32 v113, v113, v114, vcc
	v_cndmask_b32_e32 v116, v116, v119, vcc
	v_cndmask_b32_e32 v117, v117, v118, vcc
	v_cndmask_b32_e32 v120, v120, v123, vcc
	v_cndmask_b32_e32 v121, v121, v122, vcc
	v_cndmask_b32_e32 v124, v124, v127, vcc
	v_cndmask_b32_e32 v125, v125, v126, vcc
	v_mov_b32_e32 v98, v112
	v_mov_b32_e32 v99, v113
	v_mov_b32_e32 v102, v116
	v_mov_b32_e32 v103, v117
	v_mov_b32_e32 v106, v120
	v_mov_b32_e32 v107, v121
	v_mov_b32_e32 v110, v124
	v_mov_b32_e32 v111, v125
	global_store_dwordx4 v[200:201], v[96:99], off
	global_store_dwordx4 v[160:161], v[100:103], off
	global_store_dwordx4 v[162:163], v[104:107], off
	global_store_dwordx4 v[208:209], v[108:111], off
	v_cvt_pk_bf16_f32 v96, v140, v141
	v_cvt_pk_bf16_f32 v98, v142, v143
	v_cvt_pk_bf16_f32 v100, v136, v137
	v_cvt_pk_bf16_f32 v102, v138, v139
	v_cvt_pk_bf16_f32 v104, v132, v133
	v_cvt_pk_bf16_f32 v106, v134, v135
	v_cvt_pk_bf16_f32 v108, v128, v129
	v_cvt_pk_bf16_f32 v110, v130, v131
	v_mov_b32_dpp v97, v96 row_shl:4 row_mask:0xf bank_mask:0x5
	v_mov_b32_dpp v99, v98 row_shl:4 row_mask:0xf bank_mask:0x5
	v_mov_b32_dpp v101, v100 row_shl:4 row_mask:0xf bank_mask:0x5
	v_mov_b32_dpp v103, v102 row_shl:4 row_mask:0xf bank_mask:0x5
	v_mov_b32_dpp v105, v104 row_shl:4 row_mask:0xf bank_mask:0x5
	v_mov_b32_dpp v107, v106 row_shl:4 row_mask:0xf bank_mask:0x5
	v_mov_b32_dpp v109, v108 row_shl:4 row_mask:0xf bank_mask:0x5
	v_mov_b32_dpp v111, v110 row_shl:4 row_mask:0xf bank_mask:0x5
	v_mov_b32_dpp v97, v96 row_shr:4 row_mask:0xf bank_mask:0xa
	v_mov_b32_dpp v99, v98 row_shr:4 row_mask:0xf bank_mask:0xa
	v_mov_b32_dpp v101, v100 row_shr:4 row_mask:0xf bank_mask:0xa
	v_mov_b32_dpp v103, v102 row_shr:4 row_mask:0xf bank_mask:0xa
	v_mov_b32_dpp v105, v104 row_shr:4 row_mask:0xf bank_mask:0xa
	v_mov_b32_dpp v107, v106 row_shr:4 row_mask:0xf bank_mask:0xa
	v_mov_b32_dpp v109, v108 row_shr:4 row_mask:0xf bank_mask:0xa
	v_mov_b32_dpp v111, v110 row_shr:4 row_mask:0xf bank_mask:0xa
	v_perm_b32 v96, v97, v96, v193
	v_perm_b32 v98, v99, v98, v193
	v_perm_b32 v100, v101, v100, v193
	v_perm_b32 v102, v103, v102, v193
	v_perm_b32 v104, v105, v104, v193
	v_perm_b32 v106, v107, v106, v193
	v_perm_b32 v108, v109, v108, v193
	v_perm_b32 v110, v111, v110, v193
	v_mov_b32_dpp v97, v96 row_ror:8 row_mask:0xf bank_mask:0xf
	v_mov_b32_dpp v99, v98 row_ror:8 row_mask:0xf bank_mask:0xf
	v_mov_b32_dpp v101, v100 row_ror:8 row_mask:0xf bank_mask:0xf
	v_mov_b32_dpp v103, v102 row_ror:8 row_mask:0xf bank_mask:0xf
	v_mov_b32_dpp v105, v104 row_ror:8 row_mask:0xf bank_mask:0xf
	v_mov_b32_dpp v107, v106 row_ror:8 row_mask:0xf bank_mask:0xf
	v_mov_b32_dpp v109, v108 row_ror:8 row_mask:0xf bank_mask:0xf
	v_mov_b32_dpp v111, v110 row_ror:8 row_mask:0xf bank_mask:0xf
	v_cndmask_b32_e32 v96, v96, v99, vcc
	v_cndmask_b32_e32 v97, v97, v98, vcc
	v_cndmask_b32_e32 v100, v100, v103, vcc
	v_cndmask_b32_e32 v101, v101, v102, vcc
	v_cndmask_b32_e32 v104, v104, v107, vcc
	v_cndmask_b32_e32 v105, v105, v106, vcc
	v_cndmask_b32_e32 v108, v108, v111, vcc
	v_cndmask_b32_e32 v109, v109, v110, vcc
	v_cvt_pk_bf16_f32 v112, v76, v77
	v_cvt_pk_bf16_f32 v114, v78, v79
	v_cvt_pk_bf16_f32 v116, v72, v73
	v_cvt_pk_bf16_f32 v118, v74, v75
	v_cvt_pk_bf16_f32 v120, v68, v69
	v_cvt_pk_bf16_f32 v122, v70, v71
	v_cvt_pk_bf16_f32 v124, v64, v65
	v_cvt_pk_bf16_f32 v126, v66, v67
	v_mov_b32_dpp v113, v112 row_shl:4 row_mask:0xf bank_mask:0x5
	v_mov_b32_dpp v115, v114 row_shl:4 row_mask:0xf bank_mask:0x5
	v_mov_b32_dpp v117, v116 row_shl:4 row_mask:0xf bank_mask:0x5
	v_mov_b32_dpp v119, v118 row_shl:4 row_mask:0xf bank_mask:0x5
	v_mov_b32_dpp v121, v120 row_shl:4 row_mask:0xf bank_mask:0x5
	v_mov_b32_dpp v123, v122 row_shl:4 row_mask:0xf bank_mask:0x5
	v_mov_b32_dpp v125, v124 row_shl:4 row_mask:0xf bank_mask:0x5
	v_mov_b32_dpp v127, v126 row_shl:4 row_mask:0xf bank_mask:0x5
	v_mov_b32_dpp v113, v112 row_shr:4 row_mask:0xf bank_mask:0xa
	v_mov_b32_dpp v115, v114 row_shr:4 row_mask:0xf bank_mask:0xa
	v_mov_b32_dpp v117, v116 row_shr:4 row_mask:0xf bank_mask:0xa
	v_mov_b32_dpp v119, v118 row_shr:4 row_mask:0xf bank_mask:0xa
	v_mov_b32_dpp v121, v120 row_shr:4 row_mask:0xf bank_mask:0xa
	v_mov_b32_dpp v123, v122 row_shr:4 row_mask:0xf bank_mask:0xa
	v_mov_b32_dpp v125, v124 row_shr:4 row_mask:0xf bank_mask:0xa
	v_mov_b32_dpp v127, v126 row_shr:4 row_mask:0xf bank_mask:0xa
	v_perm_b32 v112, v113, v112, v193
	v_perm_b32 v114, v115, v114, v193
	v_perm_b32 v116, v117, v116, v193
	v_perm_b32 v118, v119, v118, v193
	v_perm_b32 v120, v121, v120, v193
	v_perm_b32 v122, v123, v122, v193
	v_perm_b32 v124, v125, v124, v193
	v_perm_b32 v126, v127, v126, v193
	v_mov_b32_dpp v113, v112 row_ror:8 row_mask:0xf bank_mask:0xf
	v_mov_b32_dpp v115, v114 row_ror:8 row_mask:0xf bank_mask:0xf
	v_mov_b32_dpp v117, v116 row_ror:8 row_mask:0xf bank_mask:0xf
	v_mov_b32_dpp v119, v118 row_ror:8 row_mask:0xf bank_mask:0xf
	v_mov_b32_dpp v121, v120 row_ror:8 row_mask:0xf bank_mask:0xf
	v_mov_b32_dpp v123, v122 row_ror:8 row_mask:0xf bank_mask:0xf
	v_mov_b32_dpp v125, v124 row_ror:8 row_mask:0xf bank_mask:0xf
	v_mov_b32_dpp v127, v126 row_ror:8 row_mask:0xf bank_mask:0xf
	v_cndmask_b32_e32 v112, v112, v115, vcc
	v_cndmask_b32_e32 v113, v113, v114, vcc
	v_cndmask_b32_e32 v116, v116, v119, vcc
	v_cndmask_b32_e32 v117, v117, v118, vcc
	v_cndmask_b32_e32 v120, v120, v123, vcc
	v_cndmask_b32_e32 v121, v121, v122, vcc
	v_cndmask_b32_e32 v124, v124, v127, vcc
	v_cndmask_b32_e32 v125, v125, v126, vcc
	v_mov_b32_e32 v98, v112
	v_mov_b32_e32 v99, v113
	v_mov_b32_e32 v102, v116
	v_mov_b32_e32 v103, v117
	v_mov_b32_e32 v106, v120
	v_mov_b32_e32 v107, v121
	v_mov_b32_e32 v110, v124
	v_mov_b32_e32 v111, v125
	global_store_dwordx4 v[200:201], v[96:99], off offset:16
	global_store_dwordx4 v[160:161], v[100:103], off offset:16
	global_store_dwordx4 v[162:163], v[104:107], off offset:16
	global_store_dwordx4 v[208:209], v[108:111], off offset:16
	v_cvt_pk_bf16_f32 v96, v60, v61
	v_cvt_pk_bf16_f32 v98, v62, v63
	v_cvt_pk_bf16_f32 v100, v56, v57
	v_cvt_pk_bf16_f32 v102, v58, v59
	v_cvt_pk_bf16_f32 v104, v52, v53
	v_cvt_pk_bf16_f32 v106, v54, v55
	v_cvt_pk_bf16_f32 v108, v48, v49
	v_cvt_pk_bf16_f32 v110, v50, v51
	v_mov_b32_dpp v97, v96 row_shl:4 row_mask:0xf bank_mask:0x5
	v_mov_b32_dpp v99, v98 row_shl:4 row_mask:0xf bank_mask:0x5
	v_mov_b32_dpp v101, v100 row_shl:4 row_mask:0xf bank_mask:0x5
	v_mov_b32_dpp v103, v102 row_shl:4 row_mask:0xf bank_mask:0x5
	v_mov_b32_dpp v105, v104 row_shl:4 row_mask:0xf bank_mask:0x5
	v_mov_b32_dpp v107, v106 row_shl:4 row_mask:0xf bank_mask:0x5
	v_mov_b32_dpp v109, v108 row_shl:4 row_mask:0xf bank_mask:0x5
	v_mov_b32_dpp v111, v110 row_shl:4 row_mask:0xf bank_mask:0x5
	v_mov_b32_dpp v97, v96 row_shr:4 row_mask:0xf bank_mask:0xa
	v_mov_b32_dpp v99, v98 row_shr:4 row_mask:0xf bank_mask:0xa
	v_mov_b32_dpp v101, v100 row_shr:4 row_mask:0xf bank_mask:0xa
	v_mov_b32_dpp v103, v102 row_shr:4 row_mask:0xf bank_mask:0xa
	v_mov_b32_dpp v105, v104 row_shr:4 row_mask:0xf bank_mask:0xa
	v_mov_b32_dpp v107, v106 row_shr:4 row_mask:0xf bank_mask:0xa
	v_mov_b32_dpp v109, v108 row_shr:4 row_mask:0xf bank_mask:0xa
	v_mov_b32_dpp v111, v110 row_shr:4 row_mask:0xf bank_mask:0xa
	v_perm_b32 v96, v97, v96, v193
	v_perm_b32 v98, v99, v98, v193
	v_perm_b32 v100, v101, v100, v193
	v_perm_b32 v102, v103, v102, v193
	v_perm_b32 v104, v105, v104, v193
	v_perm_b32 v106, v107, v106, v193
	v_perm_b32 v108, v109, v108, v193
	v_perm_b32 v110, v111, v110, v193
	v_mov_b32_dpp v97, v96 row_ror:8 row_mask:0xf bank_mask:0xf
	v_mov_b32_dpp v99, v98 row_ror:8 row_mask:0xf bank_mask:0xf
	v_mov_b32_dpp v101, v100 row_ror:8 row_mask:0xf bank_mask:0xf
	v_mov_b32_dpp v103, v102 row_ror:8 row_mask:0xf bank_mask:0xf
	v_mov_b32_dpp v105, v104 row_ror:8 row_mask:0xf bank_mask:0xf
	v_mov_b32_dpp v107, v106 row_ror:8 row_mask:0xf bank_mask:0xf
	v_mov_b32_dpp v109, v108 row_ror:8 row_mask:0xf bank_mask:0xf
	v_mov_b32_dpp v111, v110 row_ror:8 row_mask:0xf bank_mask:0xf
	v_cndmask_b32_e32 v96, v96, v99, vcc
	v_cndmask_b32_e32 v97, v97, v98, vcc
	v_cndmask_b32_e32 v100, v100, v103, vcc
	v_cndmask_b32_e32 v101, v101, v102, vcc
	v_cndmask_b32_e32 v104, v104, v107, vcc
	v_cndmask_b32_e32 v105, v105, v106, vcc
	v_cndmask_b32_e32 v108, v108, v111, vcc
	v_cndmask_b32_e32 v109, v109, v110, vcc
	v_cvt_pk_bf16_f32 v112, v28, v29
	v_cvt_pk_bf16_f32 v114, v30, v31
	v_cvt_pk_bf16_f32 v116, v24, v25
	v_cvt_pk_bf16_f32 v118, v26, v27
	v_cvt_pk_bf16_f32 v120, v20, v21
	v_cvt_pk_bf16_f32 v122, v22, v23
	v_cvt_pk_bf16_f32 v124, v16, v17
	v_cvt_pk_bf16_f32 v126, v18, v19
	v_mov_b32_dpp v113, v112 row_shl:4 row_mask:0xf bank_mask:0x5
	v_mov_b32_dpp v115, v114 row_shl:4 row_mask:0xf bank_mask:0x5
	v_mov_b32_dpp v117, v116 row_shl:4 row_mask:0xf bank_mask:0x5
	v_mov_b32_dpp v119, v118 row_shl:4 row_mask:0xf bank_mask:0x5
	v_mov_b32_dpp v121, v120 row_shl:4 row_mask:0xf bank_mask:0x5
	v_mov_b32_dpp v123, v122 row_shl:4 row_mask:0xf bank_mask:0x5
	v_mov_b32_dpp v125, v124 row_shl:4 row_mask:0xf bank_mask:0x5
	v_mov_b32_dpp v127, v126 row_shl:4 row_mask:0xf bank_mask:0x5
	v_mov_b32_dpp v113, v112 row_shr:4 row_mask:0xf bank_mask:0xa
	v_mov_b32_dpp v115, v114 row_shr:4 row_mask:0xf bank_mask:0xa
	v_mov_b32_dpp v117, v116 row_shr:4 row_mask:0xf bank_mask:0xa
	v_mov_b32_dpp v119, v118 row_shr:4 row_mask:0xf bank_mask:0xa
	v_mov_b32_dpp v121, v120 row_shr:4 row_mask:0xf bank_mask:0xa
	v_mov_b32_dpp v123, v122 row_shr:4 row_mask:0xf bank_mask:0xa
	v_mov_b32_dpp v125, v124 row_shr:4 row_mask:0xf bank_mask:0xa
	v_mov_b32_dpp v127, v126 row_shr:4 row_mask:0xf bank_mask:0xa
	v_perm_b32 v112, v113, v112, v193
	v_perm_b32 v114, v115, v114, v193
	v_perm_b32 v116, v117, v116, v193
	v_perm_b32 v118, v119, v118, v193
	v_perm_b32 v120, v121, v120, v193
	v_perm_b32 v122, v123, v122, v193
	v_perm_b32 v124, v125, v124, v193
	v_perm_b32 v126, v127, v126, v193
	v_mov_b32_dpp v113, v112 row_ror:8 row_mask:0xf bank_mask:0xf
	v_mov_b32_dpp v115, v114 row_ror:8 row_mask:0xf bank_mask:0xf
	v_mov_b32_dpp v117, v116 row_ror:8 row_mask:0xf bank_mask:0xf
	v_mov_b32_dpp v119, v118 row_ror:8 row_mask:0xf bank_mask:0xf
	v_mov_b32_dpp v121, v120 row_ror:8 row_mask:0xf bank_mask:0xf
	v_mov_b32_dpp v123, v122 row_ror:8 row_mask:0xf bank_mask:0xf
	v_mov_b32_dpp v125, v124 row_ror:8 row_mask:0xf bank_mask:0xf
	v_mov_b32_dpp v127, v126 row_ror:8 row_mask:0xf bank_mask:0xf
	v_cndmask_b32_e32 v112, v112, v115, vcc
	v_cndmask_b32_e32 v113, v113, v114, vcc
	v_cndmask_b32_e32 v116, v116, v119, vcc
	v_cndmask_b32_e32 v117, v117, v118, vcc
	v_cndmask_b32_e32 v120, v120, v123, vcc
	v_cndmask_b32_e32 v121, v121, v122, vcc
	v_cndmask_b32_e32 v124, v124, v127, vcc
	v_cndmask_b32_e32 v125, v125, v126, vcc
	v_mov_b32_e32 v98, v112
	v_mov_b32_e32 v99, v113
	v_mov_b32_e32 v102, v116
	v_mov_b32_e32 v103, v117
	v_mov_b32_e32 v106, v120
	v_mov_b32_e32 v107, v121
	v_mov_b32_e32 v110, v124
	v_mov_b32_e32 v111, v125
	global_store_dwordx4 v[200:201], v[96:99], off offset:64
	global_store_dwordx4 v[160:161], v[100:103], off offset:64
	global_store_dwordx4 v[162:163], v[104:107], off offset:64
	global_store_dwordx4 v[208:209], v[108:111], off offset:64
	v_cvt_pk_bf16_f32 v96, v44, v45
	v_cvt_pk_bf16_f32 v98, v46, v47
	v_cvt_pk_bf16_f32 v100, v40, v41
	v_cvt_pk_bf16_f32 v102, v42, v43
	v_cvt_pk_bf16_f32 v104, v36, v37
	v_cvt_pk_bf16_f32 v106, v38, v39
	v_cvt_pk_bf16_f32 v108, v32, v33
	v_cvt_pk_bf16_f32 v110, v34, v35
	v_mov_b32_dpp v97, v96 row_shl:4 row_mask:0xf bank_mask:0x5
	v_mov_b32_dpp v99, v98 row_shl:4 row_mask:0xf bank_mask:0x5
	v_mov_b32_dpp v101, v100 row_shl:4 row_mask:0xf bank_mask:0x5
	v_mov_b32_dpp v103, v102 row_shl:4 row_mask:0xf bank_mask:0x5
	v_mov_b32_dpp v105, v104 row_shl:4 row_mask:0xf bank_mask:0x5
	v_mov_b32_dpp v107, v106 row_shl:4 row_mask:0xf bank_mask:0x5
	v_mov_b32_dpp v109, v108 row_shl:4 row_mask:0xf bank_mask:0x5
	v_mov_b32_dpp v111, v110 row_shl:4 row_mask:0xf bank_mask:0x5
	v_mov_b32_dpp v97, v96 row_shr:4 row_mask:0xf bank_mask:0xa
	v_mov_b32_dpp v99, v98 row_shr:4 row_mask:0xf bank_mask:0xa
	v_mov_b32_dpp v101, v100 row_shr:4 row_mask:0xf bank_mask:0xa
	v_mov_b32_dpp v103, v102 row_shr:4 row_mask:0xf bank_mask:0xa
	v_mov_b32_dpp v105, v104 row_shr:4 row_mask:0xf bank_mask:0xa
	v_mov_b32_dpp v107, v106 row_shr:4 row_mask:0xf bank_mask:0xa
	v_mov_b32_dpp v109, v108 row_shr:4 row_mask:0xf bank_mask:0xa
	v_mov_b32_dpp v111, v110 row_shr:4 row_mask:0xf bank_mask:0xa
	v_perm_b32 v96, v97, v96, v193
	v_perm_b32 v98, v99, v98, v193
	v_perm_b32 v100, v101, v100, v193
	v_perm_b32 v102, v103, v102, v193
	v_perm_b32 v104, v105, v104, v193
	v_perm_b32 v106, v107, v106, v193
	v_perm_b32 v108, v109, v108, v193
	v_perm_b32 v110, v111, v110, v193
	v_mov_b32_dpp v97, v96 row_ror:8 row_mask:0xf bank_mask:0xf
	v_mov_b32_dpp v99, v98 row_ror:8 row_mask:0xf bank_mask:0xf
	v_mov_b32_dpp v101, v100 row_ror:8 row_mask:0xf bank_mask:0xf
	v_mov_b32_dpp v103, v102 row_ror:8 row_mask:0xf bank_mask:0xf
	v_mov_b32_dpp v105, v104 row_ror:8 row_mask:0xf bank_mask:0xf
	v_mov_b32_dpp v107, v106 row_ror:8 row_mask:0xf bank_mask:0xf
	v_mov_b32_dpp v109, v108 row_ror:8 row_mask:0xf bank_mask:0xf
	v_mov_b32_dpp v111, v110 row_ror:8 row_mask:0xf bank_mask:0xf
	v_cndmask_b32_e32 v96, v96, v99, vcc
	v_cndmask_b32_e32 v97, v97, v98, vcc
	v_cndmask_b32_e32 v100, v100, v103, vcc
	v_cndmask_b32_e32 v101, v101, v102, vcc
	v_cndmask_b32_e32 v104, v104, v107, vcc
	v_cndmask_b32_e32 v105, v105, v106, vcc
	v_cndmask_b32_e32 v108, v108, v111, vcc
	v_cndmask_b32_e32 v109, v109, v110, vcc
	v_cvt_pk_bf16_f32 v112, v12, v13
	v_cvt_pk_bf16_f32 v114, v14, v15
	v_cvt_pk_bf16_f32 v116, v8, v9
	v_cvt_pk_bf16_f32 v118, v10, v11
	v_cvt_pk_bf16_f32 v120, v4, v5
	v_cvt_pk_bf16_f32 v122, v6, v7
	v_cvt_pk_bf16_f32 v124, v0, v1
	v_cvt_pk_bf16_f32 v126, v2, v3
	v_mov_b32_dpp v113, v112 row_shl:4 row_mask:0xf bank_mask:0x5
	v_mov_b32_dpp v115, v114 row_shl:4 row_mask:0xf bank_mask:0x5
	v_mov_b32_dpp v117, v116 row_shl:4 row_mask:0xf bank_mask:0x5
	v_mov_b32_dpp v119, v118 row_shl:4 row_mask:0xf bank_mask:0x5
	v_mov_b32_dpp v121, v120 row_shl:4 row_mask:0xf bank_mask:0x5
	v_mov_b32_dpp v123, v122 row_shl:4 row_mask:0xf bank_mask:0x5
	v_mov_b32_dpp v125, v124 row_shl:4 row_mask:0xf bank_mask:0x5
	v_mov_b32_dpp v127, v126 row_shl:4 row_mask:0xf bank_mask:0x5
	v_mov_b32_dpp v113, v112 row_shr:4 row_mask:0xf bank_mask:0xa
	v_mov_b32_dpp v115, v114 row_shr:4 row_mask:0xf bank_mask:0xa
	v_mov_b32_dpp v117, v116 row_shr:4 row_mask:0xf bank_mask:0xa
	v_mov_b32_dpp v119, v118 row_shr:4 row_mask:0xf bank_mask:0xa
	v_mov_b32_dpp v121, v120 row_shr:4 row_mask:0xf bank_mask:0xa
	v_mov_b32_dpp v123, v122 row_shr:4 row_mask:0xf bank_mask:0xa
	v_mov_b32_dpp v125, v124 row_shr:4 row_mask:0xf bank_mask:0xa
	v_mov_b32_dpp v127, v126 row_shr:4 row_mask:0xf bank_mask:0xa
	v_perm_b32 v112, v113, v112, v193
	v_perm_b32 v114, v115, v114, v193
	v_perm_b32 v116, v117, v116, v193
	v_perm_b32 v118, v119, v118, v193
	v_perm_b32 v120, v121, v120, v193
	v_perm_b32 v122, v123, v122, v193
	v_perm_b32 v124, v125, v124, v193
	v_perm_b32 v126, v127, v126, v193
	v_mov_b32_dpp v113, v112 row_ror:8 row_mask:0xf bank_mask:0xf
	v_mov_b32_dpp v115, v114 row_ror:8 row_mask:0xf bank_mask:0xf
	v_mov_b32_dpp v117, v116 row_ror:8 row_mask:0xf bank_mask:0xf
	v_mov_b32_dpp v119, v118 row_ror:8 row_mask:0xf bank_mask:0xf
	v_mov_b32_dpp v121, v120 row_ror:8 row_mask:0xf bank_mask:0xf
	v_mov_b32_dpp v123, v122 row_ror:8 row_mask:0xf bank_mask:0xf
	v_mov_b32_dpp v125, v124 row_ror:8 row_mask:0xf bank_mask:0xf
	v_mov_b32_dpp v127, v126 row_ror:8 row_mask:0xf bank_mask:0xf
	v_cndmask_b32_e32 v112, v112, v115, vcc
	v_cndmask_b32_e32 v113, v113, v114, vcc
	v_cndmask_b32_e32 v116, v116, v119, vcc
	v_cndmask_b32_e32 v117, v117, v118, vcc
	v_cndmask_b32_e32 v120, v120, v123, vcc
	v_cndmask_b32_e32 v121, v121, v122, vcc
	v_cndmask_b32_e32 v124, v124, v127, vcc
	v_cndmask_b32_e32 v125, v125, v126, vcc
	v_mov_b32_e32 v98, v112
	v_mov_b32_e32 v99, v113
	v_mov_b32_e32 v102, v116
	v_mov_b32_e32 v103, v117
	v_mov_b32_e32 v106, v120
	v_mov_b32_e32 v107, v121
	v_mov_b32_e32 v110, v124
	v_mov_b32_e32 v111, v125
	global_store_dwordx4 v[200:201], v[96:99], off offset:80
	global_store_dwordx4 v[160:161], v[100:103], off offset:80
	global_store_dwordx4 v[162:163], v[104:107], off offset:80
	global_store_dwordx4 v[208:209], v[108:111], off offset:80
	s_mov_b64 s[0:1], 0
	s_branch .LBB0_758
.Lvt_n1_P9:
	v_lshl_add_u64 v[160:161], v[194:195], 3, s[10:11]
	global_load_dwordx2 v[162:163], v[160:161], off offset:128
	global_load_dwordx2 v[208:209], v[160:161], off offset:256
	global_load_dwordx2 v[210:211], v[160:161], off offset:384
	global_load_dwordx2 v[200:201], v[160:161], off offset:1024
	global_load_dwordx2 v[252:253], v[160:161], off offset:1152
	global_load_dwordx2 v[254:255], v[160:161], off offset:1280
	global_load_dwordx2 v[248:249], v[160:161], off offset:1408
	s_waitcnt vmcnt(0)
	v_mul_f32_e32 v193, 0x3a800000, v196
	v_mul_f32_e32 v176, v193, v193
	v_fma_f32 v176, v197, s40, -v176
	v_add_f32_e32 v176, 0x3727c5ac, v176
	v_rsq_f32_e32 v195, v176
	v_fma_f32 v156, -v104, v193, v156
	v_fma_f32 v157, -v105, v193, v157
	v_fma_f32 v158, -v106, v193, v158
	v_fma_f32 v159, -v107, v193, v159
	v_fma_f32 v152, -v96, v193, v152
	v_fma_f32 v153, -v97, v193, v153
	v_fma_f32 v154, -v98, v193, v154
	v_fma_f32 v155, -v99, v193, v155
	v_fma_f32 v148, -v112, v193, v148
	v_fma_f32 v149, -v113, v193, v149
	v_fma_f32 v150, -v114, v193, v150
	v_fma_f32 v151, -v115, v193, v151
	v_fma_f32 v144, -v124, v193, v144
	v_fma_f32 v145, -v125, v193, v145
	v_fma_f32 v146, -v126, v193, v146
	v_fma_f32 v147, -v127, v193, v147
	v_fma_f32 v156, v156, v195, v108
	v_fma_f32 v157, v157, v195, v109
	v_fma_f32 v158, v158, v195, v110
	v_fma_f32 v159, v159, v195, v111
	v_fma_f32 v152, v152, v195, v100
	v_fma_f32 v153, v153, v195, v101
	v_fma_f32 v154, v154, v195, v102
	v_fma_f32 v155, v155, v195, v103
	v_fma_f32 v148, v148, v195, v116
	v_fma_f32 v149, v149, v195, v117
	v_fma_f32 v150, v150, v195, v118
	v_fma_f32 v151, v151, v195, v119
	v_fma_f32 v144, v144, v195, v120
	v_fma_f32 v145, v145, v195, v121
	v_fma_f32 v146, v146, v195, v122
	v_fma_f32 v147, v147, v195, v123
	v_mul_f32_e32 v193, 0x3a800000, v162
	v_mul_f32_e32 v176, v193, v193
	v_fma_f32 v176, v163, s40, -v176
	v_add_f32_e32 v176, 0x3727c5ac, v176
	v_rsq_f32_e32 v195, v176
	v_fma_f32 v140, -v104, v193, v140
	v_fma_f32 v141, -v105, v193, v141
	v_fma_f32 v142, -v106, v193, v142
	v_fma_f32 v143, -v107, v193, v143
	v_fma_f32 v136, -v96, v193, v136
	v_fma_f32 v137, -v97, v193, v137
	v_fma_f32 v138, -v98, v193, v138
	v_fma_f32 v139, -v99, v193, v139
	v_fma_f32 v132, -v112, v193, v132
	v_fma_f32 v133, -v113, v193, v133
	v_fma_f32 v134, -v114, v193, v134
	v_fma_f32 v135, -v115, v193, v135
	v_fma_f32 v128, -v124, v193, v128
	v_fma_f32 v129, -v125, v193, v129
	v_fma_f32 v130, -v126, v193, v130
	v_fma_f32 v131, -v127, v193, v131
	v_fma_f32 v140, v140, v195, v108
	v_fma_f32 v141, v141, v195, v109
	v_fma_f32 v142, v142, v195, v110
	v_fma_f32 v143, v143, v195, v111
	v_fma_f32 v136, v136, v195, v100
	v_fma_f32 v137, v137, v195, v101
	v_fma_f32 v138, v138, v195, v102
	v_fma_f32 v139, v139, v195, v103
	v_fma_f32 v132, v132, v195, v116
	v_fma_f32 v133, v133, v195, v117
	v_fma_f32 v134, v134, v195, v118
	v_fma_f32 v135, v135, v195, v119
	v_fma_f32 v128, v128, v195, v120
	v_fma_f32 v129, v129, v195, v121
	v_fma_f32 v130, v130, v195, v122
	v_fma_f32 v131, v131, v195, v123
	v_mul_f32_e32 v193, 0x3a800000, v208
	v_mul_f32_e32 v176, v193, v193
	v_fma_f32 v176, v209, s40, -v176
	v_add_f32_e32 v176, 0x3727c5ac, v176
	v_rsq_f32_e32 v195, v176
	v_fma_f32 v92, -v104, v193, v92
	v_fma_f32 v93, -v105, v193, v93
	v_fma_f32 v94, -v106, v193, v94
	v_fma_f32 v95, -v107, v193, v95
	v_fma_f32 v88, -v96, v193, v88
	v_fma_f32 v89, -v97, v193, v89
	v_fma_f32 v90, -v98, v193, v90
	v_fma_f32 v91, -v99, v193, v91
	v_fma_f32 v84, -v112, v193, v84
	v_fma_f32 v85, -v113, v193, v85
	v_fma_f32 v86, -v114, v193, v86
	v_fma_f32 v87, -v115, v193, v87
	v_fma_f32 v80, -v124, v193, v80
	v_fma_f32 v81, -v125, v193, v81
	v_fma_f32 v82, -v126, v193, v82
	v_fma_f32 v83, -v127, v193, v83
	v_fma_f32 v92, v92, v195, v108
	v_fma_f32 v93, v93, v195, v109
	v_fma_f32 v94, v94, v195, v110
	v_fma_f32 v95, v95, v195, v111
	v_fma_f32 v88, v88, v195, v100
	v_fma_f32 v89, v89, v195, v101
	v_fma_f32 v90, v90, v195, v102
	v_fma_f32 v91, v91, v195, v103
	v_fma_f32 v84, v84, v195, v116
	v_fma_f32 v85, v85, v195, v117
	v_fma_f32 v86, v86, v195, v118
	v_fma_f32 v87, v87, v195, v119
	v_fma_f32 v80, v80, v195, v120
	v_fma_f32 v81, v81, v195, v121
	v_fma_f32 v82, v82, v195, v122
	v_fma_f32 v83, v83, v195, v123
	v_mul_f32_e32 v193, 0x3a800000, v210
	v_mul_f32_e32 v176, v193, v193
	v_fma_f32 v176, v211, s40, -v176
	v_add_f32_e32 v176, 0x3727c5ac, v176
	v_rsq_f32_e32 v195, v176
	v_fma_f32 v76, -v104, v193, v76
	v_fma_f32 v77, -v105, v193, v77
	v_fma_f32 v78, -v106, v193, v78
	v_fma_f32 v79, -v107, v193, v79
	v_fma_f32 v72, -v96, v193, v72
	v_fma_f32 v73, -v97, v193, v73
	v_fma_f32 v74, -v98, v193, v74
	v_fma_f32 v75, -v99, v193, v75
	v_fma_f32 v68, -v112, v193, v68
	v_fma_f32 v69, -v113, v193, v69
	v_fma_f32 v70, -v114, v193, v70
	v_fma_f32 v71, -v115, v193, v71
	v_fma_f32 v64, -v124, v193, v64
	v_fma_f32 v65, -v125, v193, v65
	v_fma_f32 v66, -v126, v193, v66
	v_fma_f32 v67, -v127, v193, v67
	v_fma_f32 v76, v76, v195, v108
	v_fma_f32 v77, v77, v195, v109
	v_fma_f32 v78, v78, v195, v110
	v_fma_f32 v79, v79, v195, v111
	v_fma_f32 v72, v72, v195, v100
	v_fma_f32 v73, v73, v195, v101
	v_fma_f32 v74, v74, v195, v102
	v_fma_f32 v75, v75, v195, v103
	v_fma_f32 v68, v68, v195, v116
	v_fma_f32 v69, v69, v195, v117
	v_fma_f32 v70, v70, v195, v118
	v_fma_f32 v71, v71, v195, v119
	v_fma_f32 v64, v64, v195, v120
	v_fma_f32 v65, v65, v195, v121
	v_fma_f32 v66, v66, v195, v122
	v_fma_f32 v67, v67, v195, v123
	v_mul_f32_e32 v193, 0x3a800000, v200
	v_mul_f32_e32 v176, v193, v193
	v_fma_f32 v176, v201, s40, -v176
	v_add_f32_e32 v176, 0x3727c5ac, v176
	v_rsq_f32_e32 v195, v176
	v_fma_f32 v60, -v104, v193, v60
	v_fma_f32 v61, -v105, v193, v61
	v_fma_f32 v62, -v106, v193, v62
	v_fma_f32 v63, -v107, v193, v63
	v_fma_f32 v56, -v96, v193, v56
	v_fma_f32 v57, -v97, v193, v57
	v_fma_f32 v58, -v98, v193, v58
	v_fma_f32 v59, -v99, v193, v59
	v_fma_f32 v52, -v112, v193, v52
	v_fma_f32 v53, -v113, v193, v53
	v_fma_f32 v54, -v114, v193, v54
	v_fma_f32 v55, -v115, v193, v55
	v_fma_f32 v48, -v124, v193, v48
	v_fma_f32 v49, -v125, v193, v49
	v_fma_f32 v50, -v126, v193, v50
	v_fma_f32 v51, -v127, v193, v51
	v_fma_f32 v60, v60, v195, v108
	v_fma_f32 v61, v61, v195, v109
	v_fma_f32 v62, v62, v195, v110
	v_fma_f32 v63, v63, v195, v111
	v_fma_f32 v56, v56, v195, v100
	v_fma_f32 v57, v57, v195, v101
	v_fma_f32 v58, v58, v195, v102
	v_fma_f32 v59, v59, v195, v103
	v_fma_f32 v52, v52, v195, v116
	v_fma_f32 v53, v53, v195, v117
	v_fma_f32 v54, v54, v195, v118
	v_fma_f32 v55, v55, v195, v119
	v_fma_f32 v48, v48, v195, v120
	v_fma_f32 v49, v49, v195, v121
	v_fma_f32 v50, v50, v195, v122
	v_fma_f32 v51, v51, v195, v123
	v_mul_f32_e32 v193, 0x3a800000, v252
	v_mul_f32_e32 v176, v193, v193
	v_fma_f32 v176, v253, s40, -v176
	v_add_f32_e32 v176, 0x3727c5ac, v176
	v_rsq_f32_e32 v195, v176
	v_fma_f32 v44, -v104, v193, v44
	v_fma_f32 v45, -v105, v193, v45
	v_fma_f32 v46, -v106, v193, v46
	v_fma_f32 v47, -v107, v193, v47
	v_fma_f32 v40, -v96, v193, v40
	v_fma_f32 v41, -v97, v193, v41
	v_fma_f32 v42, -v98, v193, v42
	v_fma_f32 v43, -v99, v193, v43
	v_fma_f32 v36, -v112, v193, v36
	v_fma_f32 v37, -v113, v193, v37
	v_fma_f32 v38, -v114, v193, v38
	v_fma_f32 v39, -v115, v193, v39
	v_fma_f32 v32, -v124, v193, v32
	v_fma_f32 v33, -v125, v193, v33
	v_fma_f32 v34, -v126, v193, v34
	v_fma_f32 v35, -v127, v193, v35
	v_fma_f32 v44, v44, v195, v108
	v_fma_f32 v45, v45, v195, v109
	v_fma_f32 v46, v46, v195, v110
	v_fma_f32 v47, v47, v195, v111
	v_fma_f32 v40, v40, v195, v100
	v_fma_f32 v41, v41, v195, v101
	v_fma_f32 v42, v42, v195, v102
	v_fma_f32 v43, v43, v195, v103
	v_fma_f32 v36, v36, v195, v116
	v_fma_f32 v37, v37, v195, v117
	v_fma_f32 v38, v38, v195, v118
	v_fma_f32 v39, v39, v195, v119
	v_fma_f32 v32, v32, v195, v120
	v_fma_f32 v33, v33, v195, v121
	v_fma_f32 v34, v34, v195, v122
	v_fma_f32 v35, v35, v195, v123
	v_mul_f32_e32 v193, 0x3a800000, v254
	v_mul_f32_e32 v176, v193, v193
	v_fma_f32 v176, v255, s40, -v176
	v_add_f32_e32 v176, 0x3727c5ac, v176
	v_rsq_f32_e32 v195, v176
	v_fma_f32 v28, -v104, v193, v28
	v_fma_f32 v29, -v105, v193, v29
	v_fma_f32 v30, -v106, v193, v30
	v_fma_f32 v31, -v107, v193, v31
	v_fma_f32 v24, -v96, v193, v24
	v_fma_f32 v25, -v97, v193, v25
	v_fma_f32 v26, -v98, v193, v26
	v_fma_f32 v27, -v99, v193, v27
	v_fma_f32 v20, -v112, v193, v20
	v_fma_f32 v21, -v113, v193, v21
	v_fma_f32 v22, -v114, v193, v22
	v_fma_f32 v23, -v115, v193, v23
	v_fma_f32 v16, -v124, v193, v16
	v_fma_f32 v17, -v125, v193, v17
	v_fma_f32 v18, -v126, v193, v18
	v_fma_f32 v19, -v127, v193, v19
	v_fma_f32 v28, v28, v195, v108
	v_fma_f32 v29, v29, v195, v109
	v_fma_f32 v30, v30, v195, v110
	v_fma_f32 v31, v31, v195, v111
	v_fma_f32 v24, v24, v195, v100
	v_fma_f32 v25, v25, v195, v101
	v_fma_f32 v26, v26, v195, v102
	v_fma_f32 v27, v27, v195, v103
	v_fma_f32 v20, v20, v195, v116
	v_fma_f32 v21, v21, v195, v117
	v_fma_f32 v22, v22, v195, v118
	v_fma_f32 v23, v23, v195, v119
	v_fma_f32 v16, v16, v195, v120
	v_fma_f32 v17, v17, v195, v121
	v_fma_f32 v18, v18, v195, v122
	v_fma_f32 v19, v19, v195, v123
	v_mul_f32_e32 v193, 0x3a800000, v248
	v_mul_f32_e32 v176, v193, v193
	v_fma_f32 v176, v249, s40, -v176
	v_add_f32_e32 v176, 0x3727c5ac, v176
	v_rsq_f32_e32 v195, v176
	v_fma_f32 v12, -v104, v193, v12
	v_fma_f32 v13, -v105, v193, v13
	v_fma_f32 v14, -v106, v193, v14
	v_fma_f32 v15, -v107, v193, v15
	v_fma_f32 v8, -v96, v193, v8
	v_fma_f32 v9, -v97, v193, v9
	v_fma_f32 v10, -v98, v193, v10
	v_fma_f32 v11, -v99, v193, v11
	v_fma_f32 v4, -v112, v193, v4
	v_fma_f32 v5, -v113, v193, v5
	v_fma_f32 v6, -v114, v193, v6
	v_fma_f32 v7, -v115, v193, v7
	v_fma_f32 v0, -v124, v193, v0
	v_fma_f32 v1, -v125, v193, v1
	v_fma_f32 v2, -v126, v193, v2
	v_fma_f32 v3, -v127, v193, v3
	v_fma_f32 v12, v12, v195, v108
	v_fma_f32 v13, v13, v195, v109
	v_fma_f32 v14, v14, v195, v110
	v_fma_f32 v15, v15, v195, v111
	v_fma_f32 v8, v8, v195, v100
	v_fma_f32 v9, v9, v195, v101
	v_fma_f32 v10, v10, v195, v102
	v_fma_f32 v11, v11, v195, v103
	v_fma_f32 v4, v4, v195, v116
	v_fma_f32 v5, v5, v195, v117
	v_fma_f32 v6, v6, v195, v118
	v_fma_f32 v7, v7, v195, v119
	v_fma_f32 v0, v0, v195, v120
	v_fma_f32 v1, v1, v195, v121
	v_fma_f32 v2, v2, v195, v122
	v_fma_f32 v3, v3, v195, v123
	s_sub_i32 s45, 13, s2
	v_and_b32_e32 v162, 0x1fcf, v194
	v_lshlrev_b32_e32 v160, s45, v194
	v_and_b32_e32 v163, 0x1ffe, v160
	v_lshrrev_b32_e32 v176, s2, v162
	v_or_b32_e32 v193, v163, v176
	v_bitop3_b32 v163, v163, s72, v176 bitop3:0xc8
	v_lshlrev_b32_e32 v176, 1, v193
	v_lshrrev_b32_e32 v193, 1, v193
	v_and_b32_e32 v176, 8, v176
	v_and_b32_e32 v193, 4, v193
	v_or3_b32 v163, v176, v163, v193
	s_ashr_i32 s0, s3, 13
	s_mul_i32 s0, s0, 12
	s_add_i32 s0, s0, s43
	s_ashr_i32 s1, s0, 31
	s_lshl_b64 s[0:1], s[0:1], 20
	v_lshl_add_u64 v[160:161], v[182:183], 0, s[0:1]
	v_lshlrev_b32_e32 v176, 1, v163
	v_lshl_add_u64 v[200:201], v[160:161], 0, v[176:177]
	v_mbcnt_lo_u32_b32 v247, -1, 0
	v_mbcnt_hi_u32_b32 v247, -1, v247
	v_and_b32_e32 v176, 3, v247
	v_mul_u32_u24_e32 v176, 0x3ffe, v176
	v_add_co_u32_e32 v200, vcc, v200, v176
	s_nop 1
	v_addc_co_u32_e32 v201, vcc, 0, v201, vcc
	v_add_co_u32_e32 v160, vcc, s59, v200
	s_nop 1
	v_addc_co_u32_e32 v161, vcc, 0, v201, vcc
	v_add_co_u32_e32 v162, vcc, s74, v200
	s_nop 1
	v_addc_co_u32_e32 v163, vcc, 0, v201, vcc
	v_add_co_u32_e32 v208, vcc, s78, v200
	s_nop 1
	v_addc_co_u32_e32 v209, vcc, 0, v201, vcc
	v_and_b32_e32 v176, 1, v247
	v_mov_b32_e32 v193, 0x5040100
	v_mov_b32_e32 v195, 0x3020706
	v_cmp_ne_u32_e32 vcc, 0, v176
	v_and_b32_e32 v176, 2, v247
	s_nop 1
	v_cndmask_b32_e32 v193, v193, v195, vcc
	v_cmp_ne_u32_e32 vcc, 0, v176
	s_nop 1
	v_cvt_pk_bf16_f32 v96, v156, v157
	v_cvt_pk_bf16_f32 v98, v158, v159
	v_cvt_pk_bf16_f32 v100, v152, v153
	v_cvt_pk_bf16_f32 v102, v154, v155
	v_cvt_pk_bf16_f32 v104, v148, v149
	v_cvt_pk_bf16_f32 v106, v150, v151
	v_cvt_pk_bf16_f32 v108, v144, v145
	v_cvt_pk_bf16_f32 v110, v146, v147
	v_mov_b32_dpp v97, v96 quad_perm:[1,0,3,2] row_mask:0xf bank_mask:0xf
	v_mov_b32_dpp v99, v98 quad_perm:[1,0,3,2] row_mask:0xf bank_mask:0xf
	v_mov_b32_dpp v101, v100 quad_perm:[1,0,3,2] row_mask:0xf bank_mask:0xf
	v_mov_b32_dpp v103, v102 quad_perm:[1,0,3,2] row_mask:0xf bank_mask:0xf
	v_mov_b32_dpp v105, v104 quad_perm:[1,0,3,2] row_mask:0xf bank_mask:0xf
	v_mov_b32_dpp v107, v106 quad_perm:[1,0,3,2] row_mask:0xf bank_mask:0xf
	v_mov_b32_dpp v109, v108 quad_perm:[1,0,3,2] row_mask:0xf bank_mask:0xf
	v_mov_b32_dpp v111, v110 quad_perm:[1,0,3,2] row_mask:0xf bank_mask:0xf
	v_perm_b32 v96, v97, v96, v193
	v_perm_b32 v98, v99, v98, v193
	v_perm_b32 v100, v101, v100, v193
	v_perm_b32 v102, v103, v102, v193
	v_perm_b32 v104, v105, v104, v193
	v_perm_b32 v106, v107, v106, v193
	v_perm_b32 v108, v109, v108, v193
	v_perm_b32 v110, v111, v110, v193
	v_mov_b32_dpp v97, v96 quad_perm:[2,3,0,1] row_mask:0xf bank_mask:0xf
	v_mov_b32_dpp v99, v98 quad_perm:[2,3,0,1] row_mask:0xf bank_mask:0xf
	v_mov_b32_dpp v101, v100 quad_perm:[2,3,0,1] row_mask:0xf bank_mask:0xf
	v_mov_b32_dpp v103, v102 quad_perm:[2,3,0,1] row_mask:0xf bank_mask:0xf
	v_mov_b32_dpp v105, v104 quad_perm:[2,3,0,1] row_mask:0xf bank_mask:0xf
	v_mov_b32_dpp v107, v106 quad_perm:[2,3,0,1] row_mask:0xf bank_mask:0xf
	v_mov_b32_dpp v109, v108 quad_perm:[2,3,0,1] row_mask:0xf bank_mask:0xf
	v_mov_b32_dpp v111, v110 quad_perm:[2,3,0,1] row_mask:0xf bank_mask:0xf
	v_cndmask_b32_e32 v96, v96, v99, vcc
	v_cndmask_b32_e32 v97, v97, v98, vcc
	v_cndmask_b32_e32 v100, v100, v103, vcc
	v_cndmask_b32_e32 v101, v101, v102, vcc
	v_cndmask_b32_e32 v104, v104, v107, vcc
	v_cndmask_b32_e32 v105, v105, v106, vcc
	v_cndmask_b32_e32 v108, v108, v111, vcc
	v_cndmask_b32_e32 v109, v109, v110, vcc
	global_store_dwordx2 v[200:201], v[96:97], off
	global_store_dwordx2 v[160:161], v[100:101], off
	global_store_dwordx2 v[162:163], v[104:105], off
	global_store_dwordx2 v[208:209], v[108:109], off
	v_cvt_pk_bf16_f32 v112, v140, v141
	v_cvt_pk_bf16_f32 v114, v142, v143
	v_cvt_pk_bf16_f32 v116, v136, v137
	v_cvt_pk_bf16_f32 v118, v138, v139
	v_cvt_pk_bf16_f32 v120, v132, v133
	v_cvt_pk_bf16_f32 v122, v134, v135
	v_cvt_pk_bf16_f32 v124, v128, v129
	v_cvt_pk_bf16_f32 v126, v130, v131
	v_mov_b32_dpp v113, v112 quad_perm:[1,0,3,2] row_mask:0xf bank_mask:0xf
	v_mov_b32_dpp v115, v114 quad_perm:[1,0,3,2] row_mask:0xf bank_mask:0xf
	v_mov_b32_dpp v117, v116 quad_perm:[1,0,3,2] row_mask:0xf bank_mask:0xf
	v_mov_b32_dpp v119, v118 quad_perm:[1,0,3,2] row_mask:0xf bank_mask:0xf
	v_mov_b32_dpp v121, v120 quad_perm:[1,0,3,2] row_mask:0xf bank_mask:0xf
	v_mov_b32_dpp v123, v122 quad_perm:[1,0,3,2] row_mask:0xf bank_mask:0xf
	v_mov_b32_dpp v125, v124 quad_perm:[1,0,3,2] row_mask:0xf bank_mask:0xf
	v_mov_b32_dpp v127, v126 quad_perm:[1,0,3,2] row_mask:0xf bank_mask:0xf
	v_perm_b32 v112, v113, v112, v193
	v_perm_b32 v114, v115, v114, v193
	v_perm_b32 v116, v117, v116, v193
	v_perm_b32 v118, v119, v118, v193
	v_perm_b32 v120, v121, v120, v193
	v_perm_b32 v122, v123, v122, v193
	v_perm_b32 v124, v125, v124, v193
	v_perm_b32 v126, v127, v126, v193
	v_mov_b32_dpp v113, v112 quad_perm:[2,3,0,1] row_mask:0xf bank_mask:0xf
	v_mov_b32_dpp v115, v114 quad_perm:[2,3,0,1] row_mask:0xf bank_mask:0xf
	v_mov_b32_dpp v117, v116 quad_perm:[2,3,0,1] row_mask:0xf bank_mask:0xf
	v_mov_b32_dpp v119, v118 quad_perm:[2,3,0,1] row_mask:0xf bank_mask:0xf
	v_mov_b32_dpp v121, v120 quad_perm:[2,3,0,1] row_mask:0xf bank_mask:0xf
	v_mov_b32_dpp v123, v122 quad_perm:[2,3,0,1] row_mask:0xf bank_mask:0xf
	v_mov_b32_dpp v125, v124 quad_perm:[2,3,0,1] row_mask:0xf bank_mask:0xf
	v_mov_b32_dpp v127, v126 quad_perm:[2,3,0,1] row_mask:0xf bank_mask:0xf
	v_cndmask_b32_e32 v112, v112, v115, vcc
	v_cndmask_b32_e32 v113, v113, v114, vcc
	v_cndmask_b32_e32 v116, v116, v119, vcc
	v_cndmask_b32_e32 v117, v117, v118, vcc
	v_cndmask_b32_e32 v120, v120, v123, vcc
	v_cndmask_b32_e32 v121, v121, v122, vcc
	v_cndmask_b32_e32 v124, v124, v127, vcc
	v_cndmask_b32_e32 v125, v125, v126, vcc
	global_store_dwordx2 v[200:201], v[112:113], off offset:32
	global_store_dwordx2 v[160:161], v[116:117], off offset:32
	global_store_dwordx2 v[162:163], v[120:121], off offset:32
	global_store_dwordx2 v[208:209], v[124:125], off offset:32
	v_cvt_pk_bf16_f32 v96, v92, v93
	v_cvt_pk_bf16_f32 v98, v94, v95
	v_cvt_pk_bf16_f32 v100, v88, v89
	v_cvt_pk_bf16_f32 v102, v90, v91
	v_cvt_pk_bf16_f32 v104, v84, v85
	v_cvt_pk_bf16_f32 v106, v86, v87
	v_cvt_pk_bf16_f32 v108, v80, v81
	v_cvt_pk_bf16_f32 v110, v82, v83
	v_mov_b32_dpp v97, v96 quad_perm:[1,0,3,2] row_mask:0xf bank_mask:0xf
	v_mov_b32_dpp v99, v98 quad_perm:[1,0,3,2] row_mask:0xf bank_mask:0xf
	v_mov_b32_dpp v101, v100 quad_perm:[1,0,3,2] row_mask:0xf bank_mask:0xf
	v_mov_b32_dpp v103, v102 quad_perm:[1,0,3,2] row_mask:0xf bank_mask:0xf
	v_mov_b32_dpp v105, v104 quad_perm:[1,0,3,2] row_mask:0xf bank_mask:0xf
	v_mov_b32_dpp v107, v106 quad_perm:[1,0,3,2] row_mask:0xf bank_mask:0xf
	v_mov_b32_dpp v109, v108 quad_perm:[1,0,3,2] row_mask:0xf bank_mask:0xf
	v_mov_b32_dpp v111, v110 quad_perm:[1,0,3,2] row_mask:0xf bank_mask:0xf
	v_perm_b32 v96, v97, v96, v193
	v_perm_b32 v98, v99, v98, v193
	v_perm_b32 v100, v101, v100, v193
	v_perm_b32 v102, v103, v102, v193
	v_perm_b32 v104, v105, v104, v193
	v_perm_b32 v106, v107, v106, v193
	v_perm_b32 v108, v109, v108, v193
	v_perm_b32 v110, v111, v110, v193
	v_mov_b32_dpp v97, v96 quad_perm:[2,3,0,1] row_mask:0xf bank_mask:0xf
	v_mov_b32_dpp v99, v98 quad_perm:[2,3,0,1] row_mask:0xf bank_mask:0xf
	v_mov_b32_dpp v101, v100 quad_perm:[2,3,0,1] row_mask:0xf bank_mask:0xf
	v_mov_b32_dpp v103, v102 quad_perm:[2,3,0,1] row_mask:0xf bank_mask:0xf
	v_mov_b32_dpp v105, v104 quad_perm:[2,3,0,1] row_mask:0xf bank_mask:0xf
	v_mov_b32_dpp v107, v106 quad_perm:[2,3,0,1] row_mask:0xf bank_mask:0xf
	v_mov_b32_dpp v109, v108 quad_perm:[2,3,0,1] row_mask:0xf bank_mask:0xf
	v_mov_b32_dpp v111, v110 quad_perm:[2,3,0,1] row_mask:0xf bank_mask:0xf
	v_cndmask_b32_e32 v96, v96, v99, vcc
	v_cndmask_b32_e32 v97, v97, v98, vcc
	v_cndmask_b32_e32 v100, v100, v103, vcc
	v_cndmask_b32_e32 v101, v101, v102, vcc
	v_cndmask_b32_e32 v104, v104, v107, vcc
	v_cndmask_b32_e32 v105, v105, v106, vcc
	v_cndmask_b32_e32 v108, v108, v111, vcc
	v_cndmask_b32_e32 v109, v109, v110, vcc
	global_store_dwordx2 v[200:201], v[96:97], off offset:64
	global_store_dwordx2 v[160:161], v[100:101], off offset:64
	global_store_dwordx2 v[162:163], v[104:105], off offset:64
	global_store_dwordx2 v[208:209], v[108:109], off offset:64
	v_cvt_pk_bf16_f32 v112, v76, v77
	v_cvt_pk_bf16_f32 v114, v78, v79
	v_cvt_pk_bf16_f32 v116, v72, v73
	v_cvt_pk_bf16_f32 v118, v74, v75
	v_cvt_pk_bf16_f32 v120, v68, v69
	v_cvt_pk_bf16_f32 v122, v70, v71
	v_cvt_pk_bf16_f32 v124, v64, v65
	v_cvt_pk_bf16_f32 v126, v66, v67
	v_mov_b32_dpp v113, v112 quad_perm:[1,0,3,2] row_mask:0xf bank_mask:0xf
	v_mov_b32_dpp v115, v114 quad_perm:[1,0,3,2] row_mask:0xf bank_mask:0xf
	v_mov_b32_dpp v117, v116 quad_perm:[1,0,3,2] row_mask:0xf bank_mask:0xf
	v_mov_b32_dpp v119, v118 quad_perm:[1,0,3,2] row_mask:0xf bank_mask:0xf
	v_mov_b32_dpp v121, v120 quad_perm:[1,0,3,2] row_mask:0xf bank_mask:0xf
	v_mov_b32_dpp v123, v122 quad_perm:[1,0,3,2] row_mask:0xf bank_mask:0xf
	v_mov_b32_dpp v125, v124 quad_perm:[1,0,3,2] row_mask:0xf bank_mask:0xf
	v_mov_b32_dpp v127, v126 quad_perm:[1,0,3,2] row_mask:0xf bank_mask:0xf
	v_perm_b32 v112, v113, v112, v193
	v_perm_b32 v114, v115, v114, v193
	v_perm_b32 v116, v117, v116, v193
	v_perm_b32 v118, v119, v118, v193
	v_perm_b32 v120, v121, v120, v193
	v_perm_b32 v122, v123, v122, v193
	v_perm_b32 v124, v125, v124, v193
	v_perm_b32 v126, v127, v126, v193
	v_mov_b32_dpp v113, v112 quad_perm:[2,3,0,1] row_mask:0xf bank_mask:0xf
	v_mov_b32_dpp v115, v114 quad_perm:[2,3,0,1] row_mask:0xf bank_mask:0xf
	v_mov_b32_dpp v117, v116 quad_perm:[2,3,0,1] row_mask:0xf bank_mask:0xf
	v_mov_b32_dpp v119, v118 quad_perm:[2,3,0,1] row_mask:0xf bank_mask:0xf
	v_mov_b32_dpp v121, v120 quad_perm:[2,3,0,1] row_mask:0xf bank_mask:0xf
	v_mov_b32_dpp v123, v122 quad_perm:[2,3,0,1] row_mask:0xf bank_mask:0xf
	v_mov_b32_dpp v125, v124 quad_perm:[2,3,0,1] row_mask:0xf bank_mask:0xf
	v_mov_b32_dpp v127, v126 quad_perm:[2,3,0,1] row_mask:0xf bank_mask:0xf
	v_cndmask_b32_e32 v112, v112, v115, vcc
	v_cndmask_b32_e32 v113, v113, v114, vcc
	v_cndmask_b32_e32 v116, v116, v119, vcc
	v_cndmask_b32_e32 v117, v117, v118, vcc
	v_cndmask_b32_e32 v120, v120, v123, vcc
	v_cndmask_b32_e32 v121, v121, v122, vcc
	v_cndmask_b32_e32 v124, v124, v127, vcc
	v_cndmask_b32_e32 v125, v125, v126, vcc
	global_store_dwordx2 v[200:201], v[112:113], off offset:96
	global_store_dwordx2 v[160:161], v[116:117], off offset:96
	global_store_dwordx2 v[162:163], v[120:121], off offset:96
	global_store_dwordx2 v[208:209], v[124:125], off offset:96
	v_cvt_pk_bf16_f32 v96, v60, v61
	v_cvt_pk_bf16_f32 v98, v62, v63
	v_cvt_pk_bf16_f32 v100, v56, v57
	v_cvt_pk_bf16_f32 v102, v58, v59
	v_cvt_pk_bf16_f32 v104, v52, v53
	v_cvt_pk_bf16_f32 v106, v54, v55
	v_cvt_pk_bf16_f32 v108, v48, v49
	v_cvt_pk_bf16_f32 v110, v50, v51
	v_mov_b32_dpp v97, v96 quad_perm:[1,0,3,2] row_mask:0xf bank_mask:0xf
	v_mov_b32_dpp v99, v98 quad_perm:[1,0,3,2] row_mask:0xf bank_mask:0xf
	v_mov_b32_dpp v101, v100 quad_perm:[1,0,3,2] row_mask:0xf bank_mask:0xf
	v_mov_b32_dpp v103, v102 quad_perm:[1,0,3,2] row_mask:0xf bank_mask:0xf
	v_mov_b32_dpp v105, v104 quad_perm:[1,0,3,2] row_mask:0xf bank_mask:0xf
	v_mov_b32_dpp v107, v106 quad_perm:[1,0,3,2] row_mask:0xf bank_mask:0xf
	v_mov_b32_dpp v109, v108 quad_perm:[1,0,3,2] row_mask:0xf bank_mask:0xf
	v_mov_b32_dpp v111, v110 quad_perm:[1,0,3,2] row_mask:0xf bank_mask:0xf
	v_perm_b32 v96, v97, v96, v193
	v_perm_b32 v98, v99, v98, v193
	v_perm_b32 v100, v101, v100, v193
	v_perm_b32 v102, v103, v102, v193
	v_perm_b32 v104, v105, v104, v193
	v_perm_b32 v106, v107, v106, v193
	v_perm_b32 v108, v109, v108, v193
	v_perm_b32 v110, v111, v110, v193
	v_mov_b32_dpp v97, v96 quad_perm:[2,3,0,1] row_mask:0xf bank_mask:0xf
	v_mov_b32_dpp v99, v98 quad_perm:[2,3,0,1] row_mask:0xf bank_mask:0xf
	v_mov_b32_dpp v101, v100 quad_perm:[2,3,0,1] row_mask:0xf bank_mask:0xf
	v_mov_b32_dpp v103, v102 quad_perm:[2,3,0,1] row_mask:0xf bank_mask:0xf
	v_mov_b32_dpp v105, v104 quad_perm:[2,3,0,1] row_mask:0xf bank_mask:0xf
	v_mov_b32_dpp v107, v106 quad_perm:[2,3,0,1] row_mask:0xf bank_mask:0xf
	v_mov_b32_dpp v109, v108 quad_perm:[2,3,0,1] row_mask:0xf bank_mask:0xf
	v_mov_b32_dpp v111, v110 quad_perm:[2,3,0,1] row_mask:0xf bank_mask:0xf
	v_cndmask_b32_e32 v96, v96, v99, vcc
	v_cndmask_b32_e32 v97, v97, v98, vcc
	v_cndmask_b32_e32 v100, v100, v103, vcc
	v_cndmask_b32_e32 v101, v101, v102, vcc
	v_cndmask_b32_e32 v104, v104, v107, vcc
	v_cndmask_b32_e32 v105, v105, v106, vcc
	v_cndmask_b32_e32 v108, v108, v111, vcc
	v_cndmask_b32_e32 v109, v109, v110, vcc
	global_store_dwordx2 v[200:201], v[96:97], off offset:256
	global_store_dwordx2 v[160:161], v[100:101], off offset:256
	global_store_dwordx2 v[162:163], v[104:105], off offset:256
	global_store_dwordx2 v[208:209], v[108:109], off offset:256
	v_cvt_pk_bf16_f32 v112, v44, v45
	v_cvt_pk_bf16_f32 v114, v46, v47
	v_cvt_pk_bf16_f32 v116, v40, v41
	v_cvt_pk_bf16_f32 v118, v42, v43
	v_cvt_pk_bf16_f32 v120, v36, v37
	v_cvt_pk_bf16_f32 v122, v38, v39
	v_cvt_pk_bf16_f32 v124, v32, v33
	v_cvt_pk_bf16_f32 v126, v34, v35
	v_mov_b32_dpp v113, v112 quad_perm:[1,0,3,2] row_mask:0xf bank_mask:0xf
	v_mov_b32_dpp v115, v114 quad_perm:[1,0,3,2] row_mask:0xf bank_mask:0xf
	v_mov_b32_dpp v117, v116 quad_perm:[1,0,3,2] row_mask:0xf bank_mask:0xf
	v_mov_b32_dpp v119, v118 quad_perm:[1,0,3,2] row_mask:0xf bank_mask:0xf
	v_mov_b32_dpp v121, v120 quad_perm:[1,0,3,2] row_mask:0xf bank_mask:0xf
	v_mov_b32_dpp v123, v122 quad_perm:[1,0,3,2] row_mask:0xf bank_mask:0xf
	v_mov_b32_dpp v125, v124 quad_perm:[1,0,3,2] row_mask:0xf bank_mask:0xf
	v_mov_b32_dpp v127, v126 quad_perm:[1,0,3,2] row_mask:0xf bank_mask:0xf
	v_perm_b32 v112, v113, v112, v193
	v_perm_b32 v114, v115, v114, v193
	v_perm_b32 v116, v117, v116, v193
	v_perm_b32 v118, v119, v118, v193
	v_perm_b32 v120, v121, v120, v193
	v_perm_b32 v122, v123, v122, v193
	v_perm_b32 v124, v125, v124, v193
	v_perm_b32 v126, v127, v126, v193
	v_mov_b32_dpp v113, v112 quad_perm:[2,3,0,1] row_mask:0xf bank_mask:0xf
	v_mov_b32_dpp v115, v114 quad_perm:[2,3,0,1] row_mask:0xf bank_mask:0xf
	v_mov_b32_dpp v117, v116 quad_perm:[2,3,0,1] row_mask:0xf bank_mask:0xf
	v_mov_b32_dpp v119, v118 quad_perm:[2,3,0,1] row_mask:0xf bank_mask:0xf
	v_mov_b32_dpp v121, v120 quad_perm:[2,3,0,1] row_mask:0xf bank_mask:0xf
	v_mov_b32_dpp v123, v122 quad_perm:[2,3,0,1] row_mask:0xf bank_mask:0xf
	v_mov_b32_dpp v125, v124 quad_perm:[2,3,0,1] row_mask:0xf bank_mask:0xf
	v_mov_b32_dpp v127, v126 quad_perm:[2,3,0,1] row_mask:0xf bank_mask:0xf
	v_cndmask_b32_e32 v112, v112, v115, vcc
	v_cndmask_b32_e32 v113, v113, v114, vcc
	v_cndmask_b32_e32 v116, v116, v119, vcc
	v_cndmask_b32_e32 v117, v117, v118, vcc
	v_cndmask_b32_e32 v120, v120, v123, vcc
	v_cndmask_b32_e32 v121, v121, v122, vcc
	v_cndmask_b32_e32 v124, v124, v127, vcc
	v_cndmask_b32_e32 v125, v125, v126, vcc
	global_store_dwordx2 v[200:201], v[112:113], off offset:288
	global_store_dwordx2 v[160:161], v[116:117], off offset:288
	global_store_dwordx2 v[162:163], v[120:121], off offset:288
	global_store_dwordx2 v[208:209], v[124:125], off offset:288
	v_cvt_pk_bf16_f32 v96, v28, v29
	v_cvt_pk_bf16_f32 v98, v30, v31
	v_cvt_pk_bf16_f32 v100, v24, v25
	v_cvt_pk_bf16_f32 v102, v26, v27
	v_cvt_pk_bf16_f32 v104, v20, v21
	v_cvt_pk_bf16_f32 v106, v22, v23
	v_cvt_pk_bf16_f32 v108, v16, v17
	v_cvt_pk_bf16_f32 v110, v18, v19
	v_mov_b32_dpp v97, v96 quad_perm:[1,0,3,2] row_mask:0xf bank_mask:0xf
	v_mov_b32_dpp v99, v98 quad_perm:[1,0,3,2] row_mask:0xf bank_mask:0xf
	v_mov_b32_dpp v101, v100 quad_perm:[1,0,3,2] row_mask:0xf bank_mask:0xf
	v_mov_b32_dpp v103, v102 quad_perm:[1,0,3,2] row_mask:0xf bank_mask:0xf
	v_mov_b32_dpp v105, v104 quad_perm:[1,0,3,2] row_mask:0xf bank_mask:0xf
	v_mov_b32_dpp v107, v106 quad_perm:[1,0,3,2] row_mask:0xf bank_mask:0xf
	v_mov_b32_dpp v109, v108 quad_perm:[1,0,3,2] row_mask:0xf bank_mask:0xf
	v_mov_b32_dpp v111, v110 quad_perm:[1,0,3,2] row_mask:0xf bank_mask:0xf
	v_perm_b32 v96, v97, v96, v193
	v_perm_b32 v98, v99, v98, v193
	v_perm_b32 v100, v101, v100, v193
	v_perm_b32 v102, v103, v102, v193
	v_perm_b32 v104, v105, v104, v193
	v_perm_b32 v106, v107, v106, v193
	v_perm_b32 v108, v109, v108, v193
	v_perm_b32 v110, v111, v110, v193
	v_mov_b32_dpp v97, v96 quad_perm:[2,3,0,1] row_mask:0xf bank_mask:0xf
	v_mov_b32_dpp v99, v98 quad_perm:[2,3,0,1] row_mask:0xf bank_mask:0xf
	v_mov_b32_dpp v101, v100 quad_perm:[2,3,0,1] row_mask:0xf bank_mask:0xf
	v_mov_b32_dpp v103, v102 quad_perm:[2,3,0,1] row_mask:0xf bank_mask:0xf
	v_mov_b32_dpp v105, v104 quad_perm:[2,3,0,1] row_mask:0xf bank_mask:0xf
	v_mov_b32_dpp v107, v106 quad_perm:[2,3,0,1] row_mask:0xf bank_mask:0xf
	v_mov_b32_dpp v109, v108 quad_perm:[2,3,0,1] row_mask:0xf bank_mask:0xf
	v_mov_b32_dpp v111, v110 quad_perm:[2,3,0,1] row_mask:0xf bank_mask:0xf
	v_cndmask_b32_e32 v96, v96, v99, vcc
	v_cndmask_b32_e32 v97, v97, v98, vcc
	v_cndmask_b32_e32 v100, v100, v103, vcc
	v_cndmask_b32_e32 v101, v101, v102, vcc
	v_cndmask_b32_e32 v104, v104, v107, vcc
	v_cndmask_b32_e32 v105, v105, v106, vcc
	v_cndmask_b32_e32 v108, v108, v111, vcc
	v_cndmask_b32_e32 v109, v109, v110, vcc
	global_store_dwordx2 v[200:201], v[96:97], off offset:320
	global_store_dwordx2 v[160:161], v[100:101], off offset:320
	global_store_dwordx2 v[162:163], v[104:105], off offset:320
	global_store_dwordx2 v[208:209], v[108:109], off offset:320
	v_cvt_pk_bf16_f32 v112, v12, v13
	v_cvt_pk_bf16_f32 v114, v14, v15
	v_cvt_pk_bf16_f32 v116, v8, v9
	v_cvt_pk_bf16_f32 v118, v10, v11
	v_cvt_pk_bf16_f32 v120, v4, v5
	v_cvt_pk_bf16_f32 v122, v6, v7
	v_cvt_pk_bf16_f32 v124, v0, v1
	v_cvt_pk_bf16_f32 v126, v2, v3
	v_mov_b32_dpp v113, v112 quad_perm:[1,0,3,2] row_mask:0xf bank_mask:0xf
	v_mov_b32_dpp v115, v114 quad_perm:[1,0,3,2] row_mask:0xf bank_mask:0xf
	v_mov_b32_dpp v117, v116 quad_perm:[1,0,3,2] row_mask:0xf bank_mask:0xf
	v_mov_b32_dpp v119, v118 quad_perm:[1,0,3,2] row_mask:0xf bank_mask:0xf
	v_mov_b32_dpp v121, v120 quad_perm:[1,0,3,2] row_mask:0xf bank_mask:0xf
	v_mov_b32_dpp v123, v122 quad_perm:[1,0,3,2] row_mask:0xf bank_mask:0xf
	v_mov_b32_dpp v125, v124 quad_perm:[1,0,3,2] row_mask:0xf bank_mask:0xf
	v_mov_b32_dpp v127, v126 quad_perm:[1,0,3,2] row_mask:0xf bank_mask:0xf
	v_perm_b32 v112, v113, v112, v193
	v_perm_b32 v114, v115, v114, v193
	v_perm_b32 v116, v117, v116, v193
	v_perm_b32 v118, v119, v118, v193
	v_perm_b32 v120, v121, v120, v193
	v_perm_b32 v122, v123, v122, v193
	v_perm_b32 v124, v125, v124, v193
	v_perm_b32 v126, v127, v126, v193
	v_mov_b32_dpp v113, v112 quad_perm:[2,3,0,1] row_mask:0xf bank_mask:0xf
	v_mov_b32_dpp v115, v114 quad_perm:[2,3,0,1] row_mask:0xf bank_mask:0xf
	v_mov_b32_dpp v117, v116 quad_perm:[2,3,0,1] row_mask:0xf bank_mask:0xf
	v_mov_b32_dpp v119, v118 quad_perm:[2,3,0,1] row_mask:0xf bank_mask:0xf
	v_mov_b32_dpp v121, v120 quad_perm:[2,3,0,1] row_mask:0xf bank_mask:0xf
	v_mov_b32_dpp v123, v122 quad_perm:[2,3,0,1] row_mask:0xf bank_mask:0xf
	v_mov_b32_dpp v125, v124 quad_perm:[2,3,0,1] row_mask:0xf bank_mask:0xf
	v_mov_b32_dpp v127, v126 quad_perm:[2,3,0,1] row_mask:0xf bank_mask:0xf
	v_cndmask_b32_e32 v112, v112, v115, vcc
	v_cndmask_b32_e32 v113, v113, v114, vcc
	v_cndmask_b32_e32 v116, v116, v119, vcc
	v_cndmask_b32_e32 v117, v117, v118, vcc
	v_cndmask_b32_e32 v120, v120, v123, vcc
	v_cndmask_b32_e32 v121, v121, v122, vcc
	v_cndmask_b32_e32 v124, v124, v127, vcc
	v_cndmask_b32_e32 v125, v125, v126, vcc
	global_store_dwordx2 v[200:201], v[112:113], off offset:352
	global_store_dwordx2 v[160:161], v[116:117], off offset:352
	global_store_dwordx2 v[162:163], v[120:121], off offset:352
	global_store_dwordx2 v[208:209], v[124:125], off offset:352
	s_mov_b64 s[0:1], 0
	s_branch .LBB0_758
	s_sub_i32 s45, 13, s2
	v_and_b32_e32 v162, 0x1fcf, v194
	v_lshlrev_b32_e32 v160, s45, v194
	v_and_b32_e32 v163, 0x1ffe, v160
	v_lshrrev_b32_e32 v176, s2, v162
	v_or_b32_e32 v193, v163, v176
	v_bitop3_b32 v163, v163, s72, v176 bitop3:0xc8
	v_lshlrev_b32_e32 v176, 1, v193
	v_lshrrev_b32_e32 v193, 1, v193
	v_and_b32_e32 v176, 8, v176
	v_and_b32_e32 v193, 4, v193
	v_or3_b32 v163, v176, v163, v193
	s_waitcnt vmcnt(0)
	v_mul_f32_e32 v193, 0x3a800000, v196
	v_mul_f32_e32 v176, v193, v193
	v_fma_f32 v176, v197, s40, -v176
	v_or_b32_e32 v208, 16, v194
	v_add_f32_e32 v176, 0x3727c5ac, v176
	v_ashrrev_i32_e32 v209, 31, v208
	v_mul_f32_e32 v195, 0x4f800000, v176
	v_cmp_gt_f32_e32 vcc, s73, v176
	v_lshl_add_u64 v[208:209], v[208:209], 3, s[10:11]
	s_ashr_i32 s0, s3, 13
	v_cndmask_b32_e32 v195, v176, v195, vcc
	global_load_dwordx2 v[208:209], v[208:209], off
	s_mul_i32 s0, s0, 12
	v_sqrt_f32_e32 v198, v195
	s_add_i32 s0, s0, s43
	s_ashr_i32 s1, s0, 31
	s_lshl_b64 s[0:1], s[0:1], 20
	v_lshl_add_u64 v[160:161], v[182:183], 0, s[0:1]
	v_lshlrev_b32_e32 v176, 1, v163
	v_add_u32_e32 v163, -1, v198
	v_lshl_add_u64 v[200:201], v[160:161], 0, v[176:177]
	v_fma_f32 v176, -v163, v198, v195
	v_cmp_ge_f32_e64 s[0:1], 0, v176
	v_add_u32_e32 v176, 1, v198
	s_nop 0
	v_cndmask_b32_e64 v163, v198, v163, s[0:1]
	v_fma_f32 v198, -v176, v198, v195
	v_cmp_lt_f32_e64 s[0:1], 0, v198
	s_nop 1
	v_cndmask_b32_e64 v163, v163, v176, s[0:1]
	v_mul_f32_e32 v176, 0x37800000, v163
	v_cndmask_b32_e32 v163, v163, v176, vcc
	v_cmp_class_f32_e32 vcc, v195, v205
	s_nop 1
	v_cndmask_b32_e32 v163, v163, v195, vcc
	v_div_scale_f32 v176, s[0:1], v163, v163, 1.0
	v_rcp_f32_e32 v195, v176
	s_nop 0
	v_fma_f32 v198, -v176, v195, 1.0
	v_fmac_f32_e32 v195, v198, v195
	v_div_scale_f32 v198, vcc, 1.0, v163, 1.0
	v_mul_f32_e32 v207, v198, v195
	v_fma_f32 v210, -v176, v207, v198
	v_fmac_f32_e32 v207, v210, v195
	v_fma_f32 v176, -v176, v207, v198
	v_div_fmas_f32 v176, v176, v195, v207
	v_div_fixup_f32 v163, v176, v163, 1.0
	v_fma_f32 v176, -v104, v193, v156
	v_fma_f32 v176, v176, v163, v108
	v_cvt_pk_bf16_f32 v176, v176, s0
	global_store_short v[200:201], v176, off
	v_fma_f32 v176, -v105, v193, v157
	v_fma_f32 v176, v176, v163, v109
	v_add_co_u32_e32 v210, vcc, s61, v200
	v_cvt_pk_bf16_f32 v176, v176, s0
	s_nop 0
	v_addc_co_u32_e32 v211, vcc, 0, v201, vcc
	global_store_short v[210:211], v176, off
	v_fma_f32 v176, -v106, v193, v158
	v_fma_f32 v176, v176, v163, v110
	v_add_co_u32_e32 v210, vcc, s67, v200
	v_cvt_pk_bf16_f32 v176, v176, s0
	s_nop 0
	v_addc_co_u32_e32 v211, vcc, 0, v201, vcc
	global_store_short v[210:211], v176, off
	v_fma_f32 v176, -v107, v193, v159
	v_fma_f32 v176, v176, v163, v111
	v_add_co_u32_e32 v210, vcc, s71, v200
	v_cvt_pk_bf16_f32 v176, v176, s0
	s_nop 0
	v_addc_co_u32_e32 v211, vcc, 0, v201, vcc
	global_store_short v[210:211], v176, off
	v_fma_f32 v176, -v96, v193, v152
	v_fma_f32 v176, v176, v163, v100
	v_add_co_u32_e32 v210, vcc, s59, v200
	v_cvt_pk_bf16_f32 v176, v176, s0
	s_nop 0
	v_addc_co_u32_e32 v211, vcc, 0, v201, vcc
	global_store_short v[210:211], v176, off
	v_fma_f32 v176, -v97, v193, v153
	v_fma_f32 v176, v176, v163, v101
	v_add_co_u32_e32 v210, vcc, s60, v200
	v_cvt_pk_bf16_f32 v176, v176, s0
	s_nop 0
	v_addc_co_u32_e32 v211, vcc, 0, v201, vcc
	global_store_short v[210:211], v176, off
	v_fma_f32 v176, -v98, v193, v154
	v_fma_f32 v176, v176, v163, v102
	v_add_co_u32_e32 v210, vcc, s66, v200
	v_cvt_pk_bf16_f32 v176, v176, s0
	s_nop 0
	v_addc_co_u32_e32 v211, vcc, 0, v201, vcc
	global_store_short v[210:211], v176, off
	v_fma_f32 v176, -v99, v193, v155
	v_fma_f32 v176, v176, v163, v103
	v_add_co_u32_e32 v210, vcc, s68, v200
	v_cvt_pk_bf16_f32 v176, v176, s0
	s_nop 0
	v_addc_co_u32_e32 v211, vcc, 0, v201, vcc
	global_store_short v[210:211], v176, off
	v_fma_f32 v176, -v112, v193, v148
	v_fma_f32 v176, v176, v163, v116
	v_add_co_u32_e32 v210, vcc, s74, v200
	v_cvt_pk_bf16_f32 v176, v176, s0
	s_nop 0
	v_addc_co_u32_e32 v211, vcc, 0, v201, vcc
	global_store_short v[210:211], v176, off
	v_fma_f32 v176, -v113, v193, v149
	v_fma_f32 v176, v176, v163, v117
	v_add_co_u32_e32 v210, vcc, s75, v200
	v_cvt_pk_bf16_f32 v176, v176, s0
	s_nop 0
	v_addc_co_u32_e32 v211, vcc, 0, v201, vcc
	global_store_short v[210:211], v176, off
	v_fma_f32 v176, -v114, v193, v150
	v_fma_f32 v176, v176, v163, v118
	v_add_co_u32_e32 v210, vcc, s76, v200
	v_cvt_pk_bf16_f32 v176, v176, s0
	s_nop 0
	v_addc_co_u32_e32 v211, vcc, 0, v201, vcc
	global_store_short v[210:211], v176, off
	v_fma_f32 v176, -v115, v193, v151
	v_fma_f32 v176, v176, v163, v119
	v_add_co_u32_e32 v210, vcc, s77, v200
	v_cvt_pk_bf16_f32 v176, v176, s0
	s_nop 0
	v_addc_co_u32_e32 v211, vcc, 0, v201, vcc
	global_store_short v[210:211], v176, off
	v_fma_f32 v176, -v124, v193, v144
	v_fma_f32 v176, v176, v163, v120
	v_add_co_u32_e32 v210, vcc, s78, v200
	v_cvt_pk_bf16_f32 v176, v176, s0
	s_nop 0
	v_addc_co_u32_e32 v211, vcc, 0, v201, vcc
	global_store_short v[210:211], v176, off
	v_fma_f32 v176, -v125, v193, v145
	v_fma_f32 v176, v176, v163, v121
	v_add_co_u32_e32 v210, vcc, s79, v200
	v_cvt_pk_bf16_f32 v176, v176, s0
	s_nop 0
	v_addc_co_u32_e32 v211, vcc, 0, v201, vcc
	global_store_short v[210:211], v176, off
	v_fma_f32 v176, -v126, v193, v146
	v_fma_f32 v176, v176, v163, v122
	v_add_co_u32_e32 v210, vcc, s80, v200
	v_cvt_pk_bf16_f32 v176, v176, s0
	s_nop 0
	v_addc_co_u32_e32 v211, vcc, 0, v201, vcc
	global_store_short v[210:211], v176, off
	v_fma_f32 v176, -v127, v193, v147
	v_fma_f32 v163, v176, v163, v123
	v_add_co_u32_e32 v200, vcc, s81, v200
	v_cvt_pk_bf16_f32 v163, v163, s0
	s_nop 0
	v_addc_co_u32_e32 v201, vcc, 0, v201, vcc
	global_store_short v[200:201], v163, off
	v_or_b32_e32 v163, 16, v162
	v_lshlrev_b32_e32 v176, s45, v163
	v_and_b32_e32 v176, 0x1ffe, v176
	v_lshrrev_b32_e32 v163, s2, v163
	v_or_b32_e32 v193, v176, v163
	v_bitop3_b32 v163, v176, s72, v163 bitop3:0xc8
	v_lshlrev_b32_e32 v176, 1, v193
	v_lshrrev_b32_e32 v193, 1, v193
	v_and_b32_e32 v176, 8, v176
	v_and_b32_e32 v193, 4, v193
	v_or3_b32 v163, v176, v163, v193
	s_waitcnt vmcnt(16)
	v_mul_f32_e32 v193, 0x3a800000, v208
	v_mul_f32_e32 v176, v193, v193
	v_fma_f32 v176, v209, s40, -v176
	v_or_b32_e32 v208, 32, v194
	v_add_f32_e32 v176, 0x3727c5ac, v176
	v_ashrrev_i32_e32 v209, 31, v208
	v_mul_f32_e32 v195, 0x4f800000, v176
	v_cmp_gt_f32_e32 vcc, s73, v176
	v_lshl_add_u64 v[208:209], v[208:209], 3, s[10:11]
	global_load_dwordx2 v[208:209], v[208:209], off
	v_cndmask_b32_e32 v195, v176, v195, vcc
	v_sqrt_f32_e32 v198, v195
	v_lshlrev_b32_e32 v176, 1, v163
	v_lshl_add_u64 v[200:201], v[160:161], 0, v[176:177]
	v_add_u32_e32 v163, -1, v198
	v_fma_f32 v176, -v163, v198, v195
	v_cmp_ge_f32_e64 s[0:1], 0, v176
	v_add_u32_e32 v176, 1, v198
	s_nop 0
	v_cndmask_b32_e64 v163, v198, v163, s[0:1]
	v_fma_f32 v198, -v176, v198, v195
	v_cmp_lt_f32_e64 s[0:1], 0, v198
	s_nop 1
	v_cndmask_b32_e64 v163, v163, v176, s[0:1]
	v_mul_f32_e32 v176, 0x37800000, v163
	v_cndmask_b32_e32 v163, v163, v176, vcc
	v_cmp_class_f32_e32 vcc, v195, v205
	s_nop 1
	v_cndmask_b32_e32 v163, v163, v195, vcc
	v_div_scale_f32 v176, s[0:1], v163, v163, 1.0
	v_rcp_f32_e32 v195, v176
	s_nop 0
	v_fma_f32 v198, -v176, v195, 1.0
	v_fmac_f32_e32 v195, v198, v195
	v_div_scale_f32 v198, vcc, 1.0, v163, 1.0
	v_mul_f32_e32 v207, v198, v195
	v_fma_f32 v210, -v176, v207, v198
	v_fmac_f32_e32 v207, v210, v195
	v_fma_f32 v176, -v176, v207, v198
	v_div_fmas_f32 v176, v176, v195, v207
	v_div_fixup_f32 v163, v176, v163, 1.0
	v_fma_f32 v176, -v104, v193, v140
	v_fma_f32 v176, v176, v163, v108
	v_cvt_pk_bf16_f32 v176, v176, s0
	global_store_short v[200:201], v176, off
	v_fma_f32 v176, -v105, v193, v141
	v_fma_f32 v176, v176, v163, v109
	v_add_co_u32_e32 v210, vcc, s61, v200
	v_cvt_pk_bf16_f32 v176, v176, s0
	s_nop 0
	v_addc_co_u32_e32 v211, vcc, 0, v201, vcc
	global_store_short v[210:211], v176, off
	v_fma_f32 v176, -v106, v193, v142
	v_fma_f32 v176, v176, v163, v110
	v_add_co_u32_e32 v210, vcc, s67, v200
	v_cvt_pk_bf16_f32 v176, v176, s0
	s_nop 0
	v_addc_co_u32_e32 v211, vcc, 0, v201, vcc
	global_store_short v[210:211], v176, off
	v_fma_f32 v176, -v107, v193, v143
	v_fma_f32 v176, v176, v163, v111
	v_add_co_u32_e32 v210, vcc, s71, v200
	v_cvt_pk_bf16_f32 v176, v176, s0
	s_nop 0
	v_addc_co_u32_e32 v211, vcc, 0, v201, vcc
	global_store_short v[210:211], v176, off
	v_fma_f32 v176, -v96, v193, v136
	v_fma_f32 v176, v176, v163, v100
	v_add_co_u32_e32 v210, vcc, s59, v200
	v_cvt_pk_bf16_f32 v176, v176, s0
	s_nop 0
	v_addc_co_u32_e32 v211, vcc, 0, v201, vcc
	global_store_short v[210:211], v176, off
	v_fma_f32 v176, -v97, v193, v137
	v_fma_f32 v176, v176, v163, v101
	v_add_co_u32_e32 v210, vcc, s60, v200
	v_cvt_pk_bf16_f32 v176, v176, s0
	s_nop 0
	v_addc_co_u32_e32 v211, vcc, 0, v201, vcc
	global_store_short v[210:211], v176, off
	v_fma_f32 v176, -v98, v193, v138
	v_fma_f32 v176, v176, v163, v102
	v_add_co_u32_e32 v210, vcc, s66, v200
	v_cvt_pk_bf16_f32 v176, v176, s0
	s_nop 0
	v_addc_co_u32_e32 v211, vcc, 0, v201, vcc
	global_store_short v[210:211], v176, off
	v_fma_f32 v176, -v99, v193, v139
	v_fma_f32 v176, v176, v163, v103
	v_add_co_u32_e32 v210, vcc, s68, v200
	v_cvt_pk_bf16_f32 v176, v176, s0
	s_nop 0
	v_addc_co_u32_e32 v211, vcc, 0, v201, vcc
	global_store_short v[210:211], v176, off
	v_fma_f32 v176, -v112, v193, v132
	v_fma_f32 v176, v176, v163, v116
	v_add_co_u32_e32 v210, vcc, s74, v200
	v_cvt_pk_bf16_f32 v176, v176, s0
	s_nop 0
	v_addc_co_u32_e32 v211, vcc, 0, v201, vcc
	global_store_short v[210:211], v176, off
	v_fma_f32 v176, -v113, v193, v133
	v_fma_f32 v176, v176, v163, v117
	v_add_co_u32_e32 v210, vcc, s75, v200
	v_cvt_pk_bf16_f32 v176, v176, s0
	s_nop 0
	v_addc_co_u32_e32 v211, vcc, 0, v201, vcc
	global_store_short v[210:211], v176, off
	v_fma_f32 v176, -v114, v193, v134
	v_fma_f32 v176, v176, v163, v118
	v_add_co_u32_e32 v210, vcc, s76, v200
	v_cvt_pk_bf16_f32 v176, v176, s0
	s_nop 0
	v_addc_co_u32_e32 v211, vcc, 0, v201, vcc
	global_store_short v[210:211], v176, off
	v_fma_f32 v176, -v115, v193, v135
	v_fma_f32 v176, v176, v163, v119
	v_add_co_u32_e32 v210, vcc, s77, v200
	v_cvt_pk_bf16_f32 v176, v176, s0
	s_nop 0
	v_addc_co_u32_e32 v211, vcc, 0, v201, vcc
	global_store_short v[210:211], v176, off
	v_fma_f32 v176, -v124, v193, v128
	v_fma_f32 v176, v176, v163, v120
	v_add_co_u32_e32 v210, vcc, s78, v200
	v_cvt_pk_bf16_f32 v176, v176, s0
	s_nop 0
	v_addc_co_u32_e32 v211, vcc, 0, v201, vcc
	global_store_short v[210:211], v176, off
	v_fma_f32 v176, -v125, v193, v129
	v_fma_f32 v176, v176, v163, v121
	v_add_co_u32_e32 v210, vcc, s79, v200
	v_cvt_pk_bf16_f32 v176, v176, s0
	s_nop 0
	v_addc_co_u32_e32 v211, vcc, 0, v201, vcc
	global_store_short v[210:211], v176, off
	v_fma_f32 v176, -v126, v193, v130
	v_fma_f32 v176, v176, v163, v122
	v_add_co_u32_e32 v210, vcc, s80, v200
	v_cvt_pk_bf16_f32 v176, v176, s0
	s_nop 0
	v_addc_co_u32_e32 v211, vcc, 0, v201, vcc
	global_store_short v[210:211], v176, off
	v_fma_f32 v176, -v127, v193, v131
	v_fma_f32 v163, v176, v163, v123
	v_add_co_u32_e32 v200, vcc, s81, v200
	v_cvt_pk_bf16_f32 v163, v163, s0
	s_nop 0
	v_addc_co_u32_e32 v201, vcc, 0, v201, vcc
	global_store_short v[200:201], v163, off
	v_or_b32_e32 v163, 32, v162
	v_lshlrev_b32_e32 v176, s45, v163
	v_and_b32_e32 v176, 0x1ffe, v176
	v_lshrrev_b32_e32 v163, s2, v163
	v_or_b32_e32 v193, v176, v163
	v_bitop3_b32 v163, v176, s72, v163 bitop3:0xc8
	v_lshlrev_b32_e32 v176, 1, v193
	v_lshrrev_b32_e32 v193, 1, v193
	v_and_b32_e32 v176, 8, v176
	v_and_b32_e32 v193, 4, v193
	v_or3_b32 v163, v176, v163, v193
	s_waitcnt vmcnt(16)
	v_mul_f32_e32 v193, 0x3a800000, v208
	v_mul_f32_e32 v176, v193, v193
	v_or_b32_e32 v208, 48, v194
	v_fma_f32 v176, v209, s40, -v176
	v_ashrrev_i32_e32 v209, 31, v208
	v_lshl_add_u64 v[208:209], v[208:209], 3, s[10:11]
	v_add_f32_e32 v176, 0x3727c5ac, v176
	global_load_dwordx2 v[208:209], v[208:209], off
	v_mul_f32_e32 v195, 0x4f800000, v176
	v_cmp_gt_f32_e32 vcc, s73, v176
	v_or_b32_e32 v162, 48, v162
	s_nop 0
	v_cndmask_b32_e32 v195, v176, v195, vcc
	v_sqrt_f32_e32 v198, v195
	v_lshlrev_b32_e32 v176, 1, v163
	v_lshl_add_u64 v[200:201], v[160:161], 0, v[176:177]
	v_add_u32_e32 v163, -1, v198
	v_fma_f32 v176, -v163, v198, v195
	v_cmp_ge_f32_e64 s[0:1], 0, v176
	v_add_u32_e32 v176, 1, v198
	s_nop 0
	v_cndmask_b32_e64 v163, v198, v163, s[0:1]
	v_fma_f32 v198, -v176, v198, v195
	v_cmp_lt_f32_e64 s[0:1], 0, v198
	s_nop 1
	v_cndmask_b32_e64 v163, v163, v176, s[0:1]
	v_mul_f32_e32 v176, 0x37800000, v163
	v_cndmask_b32_e32 v163, v163, v176, vcc
	v_cmp_class_f32_e32 vcc, v195, v205
	s_nop 1
	v_cndmask_b32_e32 v163, v163, v195, vcc
	v_div_scale_f32 v176, s[0:1], v163, v163, 1.0
	v_rcp_f32_e32 v195, v176
	s_nop 0
	v_fma_f32 v198, -v176, v195, 1.0
	v_fmac_f32_e32 v195, v198, v195
	v_div_scale_f32 v198, vcc, 1.0, v163, 1.0
	v_mul_f32_e32 v207, v198, v195
	v_fma_f32 v210, -v176, v207, v198
	v_fmac_f32_e32 v207, v210, v195
	v_fma_f32 v176, -v176, v207, v198
	v_div_fmas_f32 v176, v176, v195, v207
	v_div_fixup_f32 v163, v176, v163, 1.0
	v_fma_f32 v176, -v104, v193, v92
	v_fma_f32 v176, v176, v163, v108
	v_cvt_pk_bf16_f32 v176, v176, s0
	global_store_short v[200:201], v176, off
	v_fma_f32 v176, -v105, v193, v93
	v_fma_f32 v176, v176, v163, v109
	v_add_co_u32_e32 v210, vcc, s61, v200
	v_cvt_pk_bf16_f32 v176, v176, s0
	s_nop 0
	v_addc_co_u32_e32 v211, vcc, 0, v201, vcc
	global_store_short v[210:211], v176, off
	v_fma_f32 v176, -v106, v193, v94
	v_fma_f32 v176, v176, v163, v110
	v_add_co_u32_e32 v210, vcc, s67, v200
	v_cvt_pk_bf16_f32 v176, v176, s0
	s_nop 0
	v_addc_co_u32_e32 v211, vcc, 0, v201, vcc
	global_store_short v[210:211], v176, off
	v_fma_f32 v176, -v107, v193, v95
	v_fma_f32 v176, v176, v163, v111
	v_add_co_u32_e32 v210, vcc, s71, v200
	v_cvt_pk_bf16_f32 v176, v176, s0
	s_nop 0
	v_addc_co_u32_e32 v211, vcc, 0, v201, vcc
	global_store_short v[210:211], v176, off
	v_fma_f32 v176, -v96, v193, v88
	v_fma_f32 v176, v176, v163, v100
	v_add_co_u32_e32 v210, vcc, s59, v200
	v_cvt_pk_bf16_f32 v176, v176, s0
	s_nop 0
	v_addc_co_u32_e32 v211, vcc, 0, v201, vcc
	global_store_short v[210:211], v176, off
	v_fma_f32 v176, -v97, v193, v89
	v_fma_f32 v176, v176, v163, v101
	v_add_co_u32_e32 v210, vcc, s60, v200
	v_cvt_pk_bf16_f32 v176, v176, s0
	s_nop 0
	v_addc_co_u32_e32 v211, vcc, 0, v201, vcc
	global_store_short v[210:211], v176, off
	v_fma_f32 v176, -v98, v193, v90
	v_fma_f32 v176, v176, v163, v102
	v_add_co_u32_e32 v210, vcc, s66, v200
	v_cvt_pk_bf16_f32 v176, v176, s0
	s_nop 0
	v_addc_co_u32_e32 v211, vcc, 0, v201, vcc
	global_store_short v[210:211], v176, off
	v_fma_f32 v176, -v99, v193, v91
	v_fma_f32 v176, v176, v163, v103
	v_add_co_u32_e32 v210, vcc, s68, v200
	v_cvt_pk_bf16_f32 v176, v176, s0
	s_nop 0
	v_addc_co_u32_e32 v211, vcc, 0, v201, vcc
	global_store_short v[210:211], v176, off
	v_fma_f32 v176, -v112, v193, v84
	v_fma_f32 v176, v176, v163, v116
	v_add_co_u32_e32 v210, vcc, s74, v200
	v_cvt_pk_bf16_f32 v176, v176, s0
	s_nop 0
	v_addc_co_u32_e32 v211, vcc, 0, v201, vcc
	global_store_short v[210:211], v176, off
	v_fma_f32 v176, -v113, v193, v85
	v_fma_f32 v176, v176, v163, v117
	v_add_co_u32_e32 v210, vcc, s75, v200
	v_cvt_pk_bf16_f32 v176, v176, s0
	s_nop 0
	v_addc_co_u32_e32 v211, vcc, 0, v201, vcc
	global_store_short v[210:211], v176, off
	v_fma_f32 v176, -v114, v193, v86
	v_fma_f32 v176, v176, v163, v118
	v_add_co_u32_e32 v210, vcc, s76, v200
	v_cvt_pk_bf16_f32 v176, v176, s0
	s_nop 0
	v_addc_co_u32_e32 v211, vcc, 0, v201, vcc
	global_store_short v[210:211], v176, off
	v_fma_f32 v176, -v115, v193, v87
	v_fma_f32 v176, v176, v163, v119
	v_add_co_u32_e32 v210, vcc, s77, v200
	v_cvt_pk_bf16_f32 v176, v176, s0
	s_nop 0
	v_addc_co_u32_e32 v211, vcc, 0, v201, vcc
	global_store_short v[210:211], v176, off
	v_fma_f32 v176, -v124, v193, v80
	v_fma_f32 v176, v176, v163, v120
	v_add_co_u32_e32 v210, vcc, s78, v200
	v_cvt_pk_bf16_f32 v176, v176, s0
	s_nop 0
	v_addc_co_u32_e32 v211, vcc, 0, v201, vcc
	global_store_short v[210:211], v176, off
	v_fma_f32 v176, -v125, v193, v81
	v_fma_f32 v176, v176, v163, v121
	v_add_co_u32_e32 v210, vcc, s79, v200
	v_cvt_pk_bf16_f32 v176, v176, s0
	s_nop 0
	v_addc_co_u32_e32 v211, vcc, 0, v201, vcc
	global_store_short v[210:211], v176, off
	v_fma_f32 v176, -v126, v193, v82
	v_fma_f32 v176, v176, v163, v122
	v_add_co_u32_e32 v210, vcc, s80, v200
	v_cvt_pk_bf16_f32 v176, v176, s0
	s_nop 0
	v_addc_co_u32_e32 v211, vcc, 0, v201, vcc
	global_store_short v[210:211], v176, off
	v_fma_f32 v176, -v127, v193, v83
	v_fma_f32 v163, v176, v163, v123
	v_add_co_u32_e32 v200, vcc, s81, v200
	v_cvt_pk_bf16_f32 v163, v163, s0
	s_nop 0
	v_addc_co_u32_e32 v201, vcc, 0, v201, vcc
	global_store_short v[200:201], v163, off
	v_lshlrev_b32_e32 v163, s45, v162
	v_and_b32_e32 v163, 0x1ffe, v163
	v_lshrrev_b32_e32 v162, s2, v162
	v_or_b32_e32 v176, v163, v162
	v_bitop3_b32 v162, v163, s72, v162 bitop3:0xc8
	v_lshlrev_b32_e32 v163, 1, v176
	v_lshrrev_b32_e32 v176, 1, v176
	v_and_b32_e32 v163, 8, v163
	v_and_b32_e32 v176, 4, v176
	s_waitcnt vmcnt(16)
	v_mul_f32_e32 v193, 0x3a800000, v208
	v_or3_b32 v162, v163, v162, v176
	v_mul_f32_e32 v163, v193, v193
	v_fma_f32 v163, v209, s40, -v163
	v_add_f32_e32 v163, 0x3727c5ac, v163
	v_mul_f32_e32 v176, 0x4f800000, v163
	v_cmp_gt_f32_e32 vcc, s73, v163
	s_nop 1
	v_cndmask_b32_e32 v163, v163, v176, vcc
	v_sqrt_f32_e32 v195, v163
	v_lshlrev_b32_e32 v176, 1, v162
	v_lshl_add_u64 v[160:161], v[160:161], 0, v[176:177]
	v_add_u32_e32 v162, 0x80, v194
	v_add_u32_e32 v176, -1, v195
	v_fma_f32 v198, -v176, v195, v163
	v_cmp_ge_f32_e64 s[0:1], 0, v198
	v_add_u32_e32 v198, 1, v195
	s_nop 0
	v_cndmask_b32_e64 v176, v195, v176, s[0:1]
	v_fma_f32 v195, -v198, v195, v163
	v_cmp_lt_f32_e64 s[0:1], 0, v195
	s_nop 1
	v_cndmask_b32_e64 v176, v176, v198, s[0:1]
	v_mul_f32_e32 v195, 0x37800000, v176
	v_cndmask_b32_e32 v176, v176, v195, vcc
	v_cmp_class_f32_e32 vcc, v163, v205
	s_nop 1
	v_cndmask_b32_e32 v176, v176, v163, vcc
	v_ashrrev_i32_e32 v163, 31, v162
	v_lshl_add_u64 v[200:201], v[162:163], 3, s[10:11]
	global_load_dwordx2 v[200:201], v[200:201], off
	v_div_scale_f32 v195, s[0:1], v176, v176, 1.0
	v_rcp_f32_e32 v198, v195
	s_nop 0
	v_fma_f32 v163, -v195, v198, 1.0
	v_fmac_f32_e32 v198, v163, v198
	v_div_scale_f32 v163, vcc, 1.0, v176, 1.0
	v_mul_f32_e32 v207, v163, v198
	v_fma_f32 v208, -v195, v207, v163
	v_fmac_f32_e32 v207, v208, v198
	v_fma_f32 v163, -v195, v207, v163
	v_div_fmas_f32 v163, v163, v198, v207
	v_div_fixup_f32 v163, v163, v176, 1.0
	v_fma_f32 v176, -v104, v193, v76
	v_fma_f32 v176, v176, v163, v108
	v_cvt_pk_bf16_f32 v176, v176, s0
	global_store_short v[160:161], v176, off
	v_fma_f32 v176, -v105, v193, v77
	v_fma_f32 v176, v176, v163, v109
	v_add_co_u32_e32 v208, vcc, s61, v160
	v_cvt_pk_bf16_f32 v176, v176, s0
	s_nop 0
	v_addc_co_u32_e32 v209, vcc, 0, v161, vcc
	global_store_short v[208:209], v176, off
	v_fma_f32 v176, -v106, v193, v78
	v_fma_f32 v176, v176, v163, v110
	v_add_co_u32_e32 v208, vcc, s67, v160
	v_cvt_pk_bf16_f32 v176, v176, s0
	s_nop 0
	v_addc_co_u32_e32 v209, vcc, 0, v161, vcc
	global_store_short v[208:209], v176, off
	v_fma_f32 v176, -v107, v193, v79
	v_fma_f32 v176, v176, v163, v111
	v_add_co_u32_e32 v208, vcc, s71, v160
	v_cvt_pk_bf16_f32 v176, v176, s0
	s_nop 0
	v_addc_co_u32_e32 v209, vcc, 0, v161, vcc
	global_store_short v[208:209], v176, off
	v_fma_f32 v176, -v96, v193, v72
	v_fma_f32 v176, v176, v163, v100
	v_add_co_u32_e32 v208, vcc, s59, v160
	v_cvt_pk_bf16_f32 v176, v176, s0
	s_nop 0
	v_addc_co_u32_e32 v209, vcc, 0, v161, vcc
	global_store_short v[208:209], v176, off
	v_fma_f32 v176, -v97, v193, v73
	v_fma_f32 v176, v176, v163, v101
	v_add_co_u32_e32 v208, vcc, s60, v160
	v_cvt_pk_bf16_f32 v176, v176, s0
	s_nop 0
	v_addc_co_u32_e32 v209, vcc, 0, v161, vcc
	global_store_short v[208:209], v176, off
	v_fma_f32 v176, -v98, v193, v74
	v_fma_f32 v176, v176, v163, v102
	v_add_co_u32_e32 v208, vcc, s66, v160
	v_cvt_pk_bf16_f32 v176, v176, s0
	s_nop 0
	v_addc_co_u32_e32 v209, vcc, 0, v161, vcc
	global_store_short v[208:209], v176, off
	v_fma_f32 v176, -v99, v193, v75
	v_fma_f32 v176, v176, v163, v103
	v_add_co_u32_e32 v208, vcc, s68, v160
	v_cvt_pk_bf16_f32 v176, v176, s0
	s_nop 0
	v_addc_co_u32_e32 v209, vcc, 0, v161, vcc
	global_store_short v[208:209], v176, off
	v_fma_f32 v176, -v112, v193, v68
	v_fma_f32 v176, v176, v163, v116
	v_add_co_u32_e32 v208, vcc, s74, v160
	v_cvt_pk_bf16_f32 v176, v176, s0
	s_nop 0
	v_addc_co_u32_e32 v209, vcc, 0, v161, vcc
	global_store_short v[208:209], v176, off
	v_fma_f32 v176, -v113, v193, v69
	v_fma_f32 v176, v176, v163, v117
	v_add_co_u32_e32 v208, vcc, s75, v160
	v_cvt_pk_bf16_f32 v176, v176, s0
	s_nop 0
	v_addc_co_u32_e32 v209, vcc, 0, v161, vcc
	global_store_short v[208:209], v176, off
	v_fma_f32 v176, -v114, v193, v70
	v_fma_f32 v176, v176, v163, v118
	v_add_co_u32_e32 v208, vcc, s76, v160
	v_cvt_pk_bf16_f32 v176, v176, s0
	s_nop 0
	v_addc_co_u32_e32 v209, vcc, 0, v161, vcc
	global_store_short v[208:209], v176, off
	v_fma_f32 v176, -v115, v193, v71
	v_fma_f32 v176, v176, v163, v119
	v_add_co_u32_e32 v208, vcc, s77, v160
	v_cvt_pk_bf16_f32 v176, v176, s0
	s_nop 0
	v_addc_co_u32_e32 v209, vcc, 0, v161, vcc
	global_store_short v[208:209], v176, off
	v_fma_f32 v176, -v124, v193, v64
	v_fma_f32 v176, v176, v163, v120
	v_add_co_u32_e32 v208, vcc, s78, v160
	v_cvt_pk_bf16_f32 v176, v176, s0
	s_nop 0
	v_addc_co_u32_e32 v209, vcc, 0, v161, vcc
	global_store_short v[208:209], v176, off
	v_fma_f32 v176, -v125, v193, v65
	v_fma_f32 v176, v176, v163, v121
	v_add_co_u32_e32 v208, vcc, s79, v160
	v_cvt_pk_bf16_f32 v176, v176, s0
	s_nop 0
	v_addc_co_u32_e32 v209, vcc, 0, v161, vcc
	global_store_short v[208:209], v176, off
	v_fma_f32 v176, -v126, v193, v66
	v_fma_f32 v176, v176, v163, v122
	v_add_co_u32_e32 v208, vcc, s80, v160
	v_cvt_pk_bf16_f32 v176, v176, s0
	s_nop 0
	v_addc_co_u32_e32 v209, vcc, 0, v161, vcc
	global_store_short v[208:209], v176, off
	v_fma_f32 v176, -v127, v193, v67
	v_fma_f32 v163, v176, v163, v123
	v_add_co_u32_e32 v160, vcc, s81, v160
	v_cvt_pk_bf16_f32 v163, v163, s0
	s_nop 0
	v_addc_co_u32_e32 v161, vcc, 0, v161, vcc
	global_store_short v[160:161], v163, off
	v_ashrrev_i32_e32 v160, 13, v162
	v_and_b32_e32 v162, 0x1fcf, v162
	v_lshlrev_b32_e32 v161, s45, v162
	v_and_b32_e32 v163, 0x1ffe, v161
	v_lshrrev_b32_e32 v176, s2, v162
	v_or_b32_e32 v193, v163, v176
	v_bitop3_b32 v163, v163, s72, v176 bitop3:0xc8
	v_lshlrev_b32_e32 v176, 1, v193
	v_lshrrev_b32_e32 v193, 1, v193
	v_and_b32_e32 v176, 8, v176
	v_and_b32_e32 v193, 4, v193
	v_or3_b32 v163, v176, v163, v193
	s_waitcnt vmcnt(16)
	v_mul_f32_e32 v193, 0x3a800000, v200
	v_mul_f32_e32 v176, v193, v193
	v_fma_f32 v176, v201, s40, -v176
	v_add_u32_e32 v208, 0x90, v194
	v_add_f32_e32 v176, 0x3727c5ac, v176
	v_ashrrev_i32_e32 v209, 31, v208
	v_mul_f32_e32 v195, 0x4f800000, v176
	v_cmp_gt_f32_e32 vcc, s73, v176
	v_lshl_add_u64 v[208:209], v[208:209], 3, s[10:11]
	global_load_dwordx2 v[208:209], v[208:209], off
	v_cndmask_b32_e32 v195, v176, v195, vcc
	v_sqrt_f32_e32 v198, v195
	v_mad_i32_i24 v160, v160, 12, s43
	v_ashrrev_i32_e32 v161, 31, v160
	v_lshlrev_b64 v[160:161], 20, v[160:161]
	v_lshl_add_u64 v[160:161], v[182:183], 0, v[160:161]
	v_lshlrev_b32_e32 v176, 1, v163
	v_add_u32_e32 v163, -1, v198
	v_lshl_add_u64 v[200:201], v[160:161], 0, v[176:177]
	v_fma_f32 v176, -v163, v198, v195
	v_cmp_ge_f32_e64 s[0:1], 0, v176
	v_add_u32_e32 v176, 1, v198
	s_nop 0
	v_cndmask_b32_e64 v163, v198, v163, s[0:1]
	v_fma_f32 v198, -v176, v198, v195
	v_cmp_lt_f32_e64 s[0:1], 0, v198
	s_nop 1
	v_cndmask_b32_e64 v163, v163, v176, s[0:1]
	v_mul_f32_e32 v176, 0x37800000, v163
	v_cndmask_b32_e32 v163, v163, v176, vcc
	v_cmp_class_f32_e32 vcc, v195, v205
	s_nop 1
	v_cndmask_b32_e32 v163, v163, v195, vcc
	v_div_scale_f32 v176, s[0:1], v163, v163, 1.0
	v_rcp_f32_e32 v195, v176
	s_nop 0
	v_fma_f32 v198, -v176, v195, 1.0
	v_fmac_f32_e32 v195, v198, v195
	v_div_scale_f32 v198, vcc, 1.0, v163, 1.0
	v_mul_f32_e32 v207, v198, v195
	v_fma_f32 v210, -v176, v207, v198
	v_fmac_f32_e32 v207, v210, v195
	v_fma_f32 v176, -v176, v207, v198
	v_div_fmas_f32 v176, v176, v195, v207
	v_div_fixup_f32 v163, v176, v163, 1.0
	v_fma_f32 v176, -v104, v193, v60
	v_fma_f32 v176, v176, v163, v108
	v_cvt_pk_bf16_f32 v176, v176, s0
	global_store_short v[200:201], v176, off
	v_fma_f32 v176, -v105, v193, v61
	v_fma_f32 v176, v176, v163, v109
	v_add_co_u32_e32 v210, vcc, s61, v200
	v_cvt_pk_bf16_f32 v176, v176, s0
	s_nop 0
	v_addc_co_u32_e32 v211, vcc, 0, v201, vcc
	global_store_short v[210:211], v176, off
	v_fma_f32 v176, -v106, v193, v62
	v_fma_f32 v176, v176, v163, v110
	v_add_co_u32_e32 v210, vcc, s67, v200
	v_cvt_pk_bf16_f32 v176, v176, s0
	s_nop 0
	v_addc_co_u32_e32 v211, vcc, 0, v201, vcc
	global_store_short v[210:211], v176, off
	v_fma_f32 v176, -v107, v193, v63
	v_fma_f32 v176, v176, v163, v111
	v_add_co_u32_e32 v210, vcc, s71, v200
	v_cvt_pk_bf16_f32 v176, v176, s0
	s_nop 0
	v_addc_co_u32_e32 v211, vcc, 0, v201, vcc
	global_store_short v[210:211], v176, off
	v_fma_f32 v176, -v96, v193, v56
	v_fma_f32 v176, v176, v163, v100
	v_add_co_u32_e32 v210, vcc, s59, v200
	v_cvt_pk_bf16_f32 v176, v176, s0
	s_nop 0
	v_addc_co_u32_e32 v211, vcc, 0, v201, vcc
	global_store_short v[210:211], v176, off
	v_fma_f32 v176, -v97, v193, v57
	v_fma_f32 v176, v176, v163, v101
	v_add_co_u32_e32 v210, vcc, s60, v200
	v_cvt_pk_bf16_f32 v176, v176, s0
	s_nop 0
	v_addc_co_u32_e32 v211, vcc, 0, v201, vcc
	global_store_short v[210:211], v176, off
	v_fma_f32 v176, -v98, v193, v58
	v_fma_f32 v176, v176, v163, v102
	v_add_co_u32_e32 v210, vcc, s66, v200
	v_cvt_pk_bf16_f32 v176, v176, s0
	s_nop 0
	v_addc_co_u32_e32 v211, vcc, 0, v201, vcc
	global_store_short v[210:211], v176, off
	v_fma_f32 v176, -v99, v193, v59
	v_fma_f32 v176, v176, v163, v103
	v_add_co_u32_e32 v210, vcc, s68, v200
	v_cvt_pk_bf16_f32 v176, v176, s0
	s_nop 0
	v_addc_co_u32_e32 v211, vcc, 0, v201, vcc
	global_store_short v[210:211], v176, off
	v_fma_f32 v176, -v112, v193, v52
	v_fma_f32 v176, v176, v163, v116
	v_add_co_u32_e32 v210, vcc, s74, v200
	v_cvt_pk_bf16_f32 v176, v176, s0
	s_nop 0
	v_addc_co_u32_e32 v211, vcc, 0, v201, vcc
	global_store_short v[210:211], v176, off
	v_fma_f32 v176, -v113, v193, v53
	v_fma_f32 v176, v176, v163, v117
	v_add_co_u32_e32 v210, vcc, s75, v200
	v_cvt_pk_bf16_f32 v176, v176, s0
	s_nop 0
	v_addc_co_u32_e32 v211, vcc, 0, v201, vcc
	global_store_short v[210:211], v176, off
	v_fma_f32 v176, -v114, v193, v54
	v_fma_f32 v176, v176, v163, v118
	v_add_co_u32_e32 v210, vcc, s76, v200
	v_cvt_pk_bf16_f32 v176, v176, s0
	s_nop 0
	v_addc_co_u32_e32 v211, vcc, 0, v201, vcc
	global_store_short v[210:211], v176, off
	v_fma_f32 v176, -v115, v193, v55
	v_fma_f32 v176, v176, v163, v119
	v_add_co_u32_e32 v210, vcc, s77, v200
	v_cvt_pk_bf16_f32 v176, v176, s0
	s_nop 0
	v_addc_co_u32_e32 v211, vcc, 0, v201, vcc
	global_store_short v[210:211], v176, off
	v_fma_f32 v176, -v124, v193, v48
	v_fma_f32 v176, v176, v163, v120
	v_add_co_u32_e32 v210, vcc, s78, v200
	v_cvt_pk_bf16_f32 v176, v176, s0
	s_nop 0
	v_addc_co_u32_e32 v211, vcc, 0, v201, vcc
	global_store_short v[210:211], v176, off
	v_fma_f32 v176, -v125, v193, v49
	v_fma_f32 v176, v176, v163, v121
	v_add_co_u32_e32 v210, vcc, s79, v200
	v_cvt_pk_bf16_f32 v176, v176, s0
	s_nop 0
	v_addc_co_u32_e32 v211, vcc, 0, v201, vcc
	global_store_short v[210:211], v176, off
	v_fma_f32 v176, -v126, v193, v50
	v_fma_f32 v176, v176, v163, v122
	v_add_co_u32_e32 v210, vcc, s80, v200
	v_cvt_pk_bf16_f32 v176, v176, s0
	s_nop 0
	v_addc_co_u32_e32 v211, vcc, 0, v201, vcc
	global_store_short v[210:211], v176, off
	v_fma_f32 v176, -v127, v193, v51
	v_fma_f32 v163, v176, v163, v123
	v_add_co_u32_e32 v200, vcc, s81, v200
	v_cvt_pk_bf16_f32 v163, v163, s0
	s_nop 0
	v_addc_co_u32_e32 v201, vcc, 0, v201, vcc
	global_store_short v[200:201], v163, off
	v_or_b32_e32 v163, 16, v162
	v_lshlrev_b32_e32 v176, s45, v163
	v_and_b32_e32 v176, 0x1ffe, v176
	v_lshrrev_b32_e32 v163, s2, v163
	v_or_b32_e32 v193, v176, v163
	v_bitop3_b32 v163, v176, s72, v163 bitop3:0xc8
	v_lshlrev_b32_e32 v176, 1, v193
	v_lshrrev_b32_e32 v193, 1, v193
	v_and_b32_e32 v176, 8, v176
	v_and_b32_e32 v193, 4, v193
	v_or3_b32 v163, v176, v163, v193
	s_waitcnt vmcnt(16)
	v_mul_f32_e32 v193, 0x3a800000, v208
	v_mul_f32_e32 v176, v193, v193
	v_fma_f32 v176, v209, s40, -v176
	v_add_u32_e32 v208, 0xa0, v194
	v_add_f32_e32 v176, 0x3727c5ac, v176
	v_ashrrev_i32_e32 v209, 31, v208
	v_mul_f32_e32 v195, 0x4f800000, v176
	v_cmp_gt_f32_e32 vcc, s73, v176
	v_lshl_add_u64 v[208:209], v[208:209], 3, s[10:11]
	global_load_dwordx2 v[208:209], v[208:209], off
	v_cndmask_b32_e32 v195, v176, v195, vcc
	v_sqrt_f32_e32 v198, v195
	v_lshlrev_b32_e32 v176, 1, v163
	v_lshl_add_u64 v[200:201], v[160:161], 0, v[176:177]
	v_add_u32_e32 v163, -1, v198
	v_fma_f32 v176, -v163, v198, v195
	v_cmp_ge_f32_e64 s[0:1], 0, v176
	v_add_u32_e32 v176, 1, v198
	s_nop 0
	v_cndmask_b32_e64 v163, v198, v163, s[0:1]
	v_fma_f32 v198, -v176, v198, v195
	v_cmp_lt_f32_e64 s[0:1], 0, v198
	s_nop 1
	v_cndmask_b32_e64 v163, v163, v176, s[0:1]
	v_mul_f32_e32 v176, 0x37800000, v163
	v_cndmask_b32_e32 v163, v163, v176, vcc
	v_cmp_class_f32_e32 vcc, v195, v205
	s_nop 1
	v_cndmask_b32_e32 v163, v163, v195, vcc
	v_div_scale_f32 v176, s[0:1], v163, v163, 1.0
	v_rcp_f32_e32 v195, v176
	s_nop 0
	v_fma_f32 v198, -v176, v195, 1.0
	v_fmac_f32_e32 v195, v198, v195
	v_div_scale_f32 v198, vcc, 1.0, v163, 1.0
	v_mul_f32_e32 v207, v198, v195
	v_fma_f32 v210, -v176, v207, v198
	v_fmac_f32_e32 v207, v210, v195
	v_fma_f32 v176, -v176, v207, v198
	v_div_fmas_f32 v176, v176, v195, v207
	v_div_fixup_f32 v163, v176, v163, 1.0
	v_fma_f32 v176, -v104, v193, v44
	v_fma_f32 v176, v176, v163, v108
	v_cvt_pk_bf16_f32 v176, v176, s0
	global_store_short v[200:201], v176, off
	v_fma_f32 v176, -v105, v193, v45
	v_fma_f32 v176, v176, v163, v109
	v_add_co_u32_e32 v210, vcc, s61, v200
	v_cvt_pk_bf16_f32 v176, v176, s0
	s_nop 0
	v_addc_co_u32_e32 v211, vcc, 0, v201, vcc
	global_store_short v[210:211], v176, off
	v_fma_f32 v176, -v106, v193, v46
	v_fma_f32 v176, v176, v163, v110
	v_add_co_u32_e32 v210, vcc, s67, v200
	v_cvt_pk_bf16_f32 v176, v176, s0
	s_nop 0
	v_addc_co_u32_e32 v211, vcc, 0, v201, vcc
	global_store_short v[210:211], v176, off
	v_fma_f32 v176, -v107, v193, v47
	v_fma_f32 v176, v176, v163, v111
	v_add_co_u32_e32 v210, vcc, s71, v200
	v_cvt_pk_bf16_f32 v176, v176, s0
	s_nop 0
	v_addc_co_u32_e32 v211, vcc, 0, v201, vcc
	global_store_short v[210:211], v176, off
	v_fma_f32 v176, -v96, v193, v40
	v_fma_f32 v176, v176, v163, v100
	v_add_co_u32_e32 v210, vcc, s59, v200
	v_cvt_pk_bf16_f32 v176, v176, s0
	s_nop 0
	v_addc_co_u32_e32 v211, vcc, 0, v201, vcc
	global_store_short v[210:211], v176, off
	v_fma_f32 v176, -v97, v193, v41
	v_fma_f32 v176, v176, v163, v101
	v_add_co_u32_e32 v210, vcc, s60, v200
	v_cvt_pk_bf16_f32 v176, v176, s0
	s_nop 0
	v_addc_co_u32_e32 v211, vcc, 0, v201, vcc
	global_store_short v[210:211], v176, off
	v_fma_f32 v176, -v98, v193, v42
	v_fma_f32 v176, v176, v163, v102
	v_add_co_u32_e32 v210, vcc, s66, v200
	v_cvt_pk_bf16_f32 v176, v176, s0
	s_nop 0
	v_addc_co_u32_e32 v211, vcc, 0, v201, vcc
	global_store_short v[210:211], v176, off
	v_fma_f32 v176, -v99, v193, v43
	v_fma_f32 v176, v176, v163, v103
	v_add_co_u32_e32 v210, vcc, s68, v200
	v_cvt_pk_bf16_f32 v176, v176, s0
	s_nop 0
	v_addc_co_u32_e32 v211, vcc, 0, v201, vcc
	global_store_short v[210:211], v176, off
	v_fma_f32 v176, -v112, v193, v36
	v_fma_f32 v176, v176, v163, v116
	v_add_co_u32_e32 v210, vcc, s74, v200
	v_cvt_pk_bf16_f32 v176, v176, s0
	s_nop 0
	v_addc_co_u32_e32 v211, vcc, 0, v201, vcc
	global_store_short v[210:211], v176, off
	v_fma_f32 v176, -v113, v193, v37
	v_fma_f32 v176, v176, v163, v117
	v_add_co_u32_e32 v210, vcc, s75, v200
	v_cvt_pk_bf16_f32 v176, v176, s0
	s_nop 0
	v_addc_co_u32_e32 v211, vcc, 0, v201, vcc
	global_store_short v[210:211], v176, off
	v_fma_f32 v176, -v114, v193, v38
	v_fma_f32 v176, v176, v163, v118
	v_add_co_u32_e32 v210, vcc, s76, v200
	v_cvt_pk_bf16_f32 v176, v176, s0
	s_nop 0
	v_addc_co_u32_e32 v211, vcc, 0, v201, vcc
	global_store_short v[210:211], v176, off
	v_fma_f32 v176, -v115, v193, v39
	v_fma_f32 v176, v176, v163, v119
	v_add_co_u32_e32 v210, vcc, s77, v200
	v_cvt_pk_bf16_f32 v176, v176, s0
	s_nop 0
	v_addc_co_u32_e32 v211, vcc, 0, v201, vcc
	global_store_short v[210:211], v176, off
	v_fma_f32 v176, -v124, v193, v32
	v_fma_f32 v176, v176, v163, v120
	v_add_co_u32_e32 v210, vcc, s78, v200
	v_cvt_pk_bf16_f32 v176, v176, s0
	s_nop 0
	v_addc_co_u32_e32 v211, vcc, 0, v201, vcc
	global_store_short v[210:211], v176, off
	v_fma_f32 v176, -v125, v193, v33
	v_fma_f32 v176, v176, v163, v121
	v_add_co_u32_e32 v210, vcc, s79, v200
	v_cvt_pk_bf16_f32 v176, v176, s0
	s_nop 0
	v_addc_co_u32_e32 v211, vcc, 0, v201, vcc
	global_store_short v[210:211], v176, off
	v_fma_f32 v176, -v126, v193, v34
	v_fma_f32 v176, v176, v163, v122
	v_add_co_u32_e32 v210, vcc, s80, v200
	v_cvt_pk_bf16_f32 v176, v176, s0
	s_nop 0
	v_addc_co_u32_e32 v211, vcc, 0, v201, vcc
	global_store_short v[210:211], v176, off
	v_fma_f32 v176, -v127, v193, v35
	v_fma_f32 v163, v176, v163, v123
	v_add_co_u32_e32 v200, vcc, s81, v200
	v_cvt_pk_bf16_f32 v163, v163, s0
	s_nop 0
	v_addc_co_u32_e32 v201, vcc, 0, v201, vcc
	global_store_short v[200:201], v163, off
	v_or_b32_e32 v163, 32, v162
	v_lshlrev_b32_e32 v176, s45, v163
	v_and_b32_e32 v176, 0x1ffe, v176
	v_lshrrev_b32_e32 v163, s2, v163
	v_or_b32_e32 v193, v176, v163
	v_bitop3_b32 v163, v176, s72, v163 bitop3:0xc8
	v_lshlrev_b32_e32 v176, 1, v193
	v_lshrrev_b32_e32 v193, 1, v193
	v_and_b32_e32 v176, 8, v176
	v_and_b32_e32 v193, 4, v193
	v_or3_b32 v163, v176, v163, v193
	s_waitcnt vmcnt(16)
	v_mul_f32_e32 v193, 0x3a800000, v208
	v_mul_f32_e32 v176, v193, v193
	v_add_u32_e32 v208, 0xb0, v194
	v_fma_f32 v176, v209, s40, -v176
	v_ashrrev_i32_e32 v209, 31, v208
	v_lshl_add_u64 v[208:209], v[208:209], 3, s[10:11]
	global_load_dwordx2 v[208:209], v[208:209], off
	v_add_f32_e32 v176, 0x3727c5ac, v176
	v_mul_f32_e32 v195, 0x4f800000, v176
	v_cmp_gt_f32_e32 vcc, s73, v176
	v_or_b32_e32 v162, 48, v162
	s_nop 0
	v_cndmask_b32_e32 v195, v176, v195, vcc
	v_sqrt_f32_e32 v198, v195
	v_lshlrev_b32_e32 v176, 1, v163
	v_lshl_add_u64 v[200:201], v[160:161], 0, v[176:177]
	v_add_u32_e32 v163, -1, v198
	v_fma_f32 v176, -v163, v198, v195
	v_cmp_ge_f32_e64 s[0:1], 0, v176
	v_add_u32_e32 v176, 1, v198
	s_nop 0
	v_cndmask_b32_e64 v163, v198, v163, s[0:1]
	v_fma_f32 v198, -v176, v198, v195
	v_cmp_lt_f32_e64 s[0:1], 0, v198
	s_nop 1
	v_cndmask_b32_e64 v163, v163, v176, s[0:1]
	v_mul_f32_e32 v176, 0x37800000, v163
	v_cndmask_b32_e32 v163, v163, v176, vcc
	v_cmp_class_f32_e32 vcc, v195, v205
	s_nop 1
	v_cndmask_b32_e32 v163, v163, v195, vcc
	v_div_scale_f32 v176, s[0:1], v163, v163, 1.0
	v_rcp_f32_e32 v195, v176
	s_nop 0
	v_fma_f32 v198, -v176, v195, 1.0
	v_fmac_f32_e32 v195, v198, v195
	v_div_scale_f32 v198, vcc, 1.0, v163, 1.0
	v_mul_f32_e32 v207, v198, v195
	v_fma_f32 v210, -v176, v207, v198
	v_fmac_f32_e32 v207, v210, v195
	v_fma_f32 v176, -v176, v207, v198
	v_div_fmas_f32 v176, v176, v195, v207
	v_div_fixup_f32 v163, v176, v163, 1.0
	v_fma_f32 v176, -v104, v193, v28
	v_fma_f32 v176, v176, v163, v108
	v_cvt_pk_bf16_f32 v176, v176, s0
	global_store_short v[200:201], v176, off
	v_fma_f32 v176, -v105, v193, v29
	v_fma_f32 v176, v176, v163, v109
	v_add_co_u32_e32 v210, vcc, s61, v200
	v_cvt_pk_bf16_f32 v176, v176, s0
	s_nop 0
	v_addc_co_u32_e32 v211, vcc, 0, v201, vcc
	global_store_short v[210:211], v176, off
	v_fma_f32 v176, -v106, v193, v30
	v_fma_f32 v176, v176, v163, v110
	v_add_co_u32_e32 v210, vcc, s67, v200
	v_cvt_pk_bf16_f32 v176, v176, s0
	s_nop 0
	v_addc_co_u32_e32 v211, vcc, 0, v201, vcc
	global_store_short v[210:211], v176, off
	v_fma_f32 v176, -v107, v193, v31
	v_fma_f32 v176, v176, v163, v111
	v_add_co_u32_e32 v210, vcc, s71, v200
	v_cvt_pk_bf16_f32 v176, v176, s0
	s_nop 0
	v_addc_co_u32_e32 v211, vcc, 0, v201, vcc
	global_store_short v[210:211], v176, off
	v_fma_f32 v176, -v96, v193, v24
	v_fma_f32 v176, v176, v163, v100
	v_add_co_u32_e32 v210, vcc, s59, v200
	v_cvt_pk_bf16_f32 v176, v176, s0
	s_nop 0
	v_addc_co_u32_e32 v211, vcc, 0, v201, vcc
	global_store_short v[210:211], v176, off
	v_fma_f32 v176, -v97, v193, v25
	v_fma_f32 v176, v176, v163, v101
	v_add_co_u32_e32 v210, vcc, s60, v200
	v_cvt_pk_bf16_f32 v176, v176, s0
	s_nop 0
	v_addc_co_u32_e32 v211, vcc, 0, v201, vcc
	global_store_short v[210:211], v176, off
	v_fma_f32 v176, -v98, v193, v26
	v_fma_f32 v176, v176, v163, v102
	v_add_co_u32_e32 v210, vcc, s66, v200
	v_cvt_pk_bf16_f32 v176, v176, s0
	s_nop 0
	v_addc_co_u32_e32 v211, vcc, 0, v201, vcc
	global_store_short v[210:211], v176, off
	v_fma_f32 v176, -v99, v193, v27
	v_fma_f32 v176, v176, v163, v103
	v_add_co_u32_e32 v210, vcc, s68, v200
	v_cvt_pk_bf16_f32 v176, v176, s0
	s_nop 0
	v_addc_co_u32_e32 v211, vcc, 0, v201, vcc
	global_store_short v[210:211], v176, off
	v_fma_f32 v176, -v112, v193, v20
	v_fma_f32 v176, v176, v163, v116
	v_add_co_u32_e32 v210, vcc, s74, v200
	v_cvt_pk_bf16_f32 v176, v176, s0
	s_nop 0
	v_addc_co_u32_e32 v211, vcc, 0, v201, vcc
	global_store_short v[210:211], v176, off
	v_fma_f32 v176, -v113, v193, v21
	v_fma_f32 v176, v176, v163, v117
	v_add_co_u32_e32 v210, vcc, s75, v200
	v_cvt_pk_bf16_f32 v176, v176, s0
	s_nop 0
	v_addc_co_u32_e32 v211, vcc, 0, v201, vcc
	global_store_short v[210:211], v176, off
	v_fma_f32 v176, -v114, v193, v22
	v_fma_f32 v176, v176, v163, v118
	v_add_co_u32_e32 v210, vcc, s76, v200
	v_cvt_pk_bf16_f32 v176, v176, s0
	s_nop 0
	v_addc_co_u32_e32 v211, vcc, 0, v201, vcc
	global_store_short v[210:211], v176, off
	v_fma_f32 v176, -v115, v193, v23
	v_fma_f32 v176, v176, v163, v119
	v_add_co_u32_e32 v210, vcc, s77, v200
	v_cvt_pk_bf16_f32 v176, v176, s0
	s_nop 0
	v_addc_co_u32_e32 v211, vcc, 0, v201, vcc
	global_store_short v[210:211], v176, off
	v_fma_f32 v176, -v124, v193, v16
	v_fma_f32 v176, v176, v163, v120
	v_add_co_u32_e32 v210, vcc, s78, v200
	v_cvt_pk_bf16_f32 v176, v176, s0
	s_nop 0
	v_addc_co_u32_e32 v211, vcc, 0, v201, vcc
	global_store_short v[210:211], v176, off
	v_fma_f32 v176, -v125, v193, v17
	v_fma_f32 v176, v176, v163, v121
	v_add_co_u32_e32 v210, vcc, s79, v200
	v_cvt_pk_bf16_f32 v176, v176, s0
	s_nop 0
	v_addc_co_u32_e32 v211, vcc, 0, v201, vcc
	global_store_short v[210:211], v176, off
	v_fma_f32 v176, -v126, v193, v18
	v_fma_f32 v176, v176, v163, v122
	v_add_co_u32_e32 v210, vcc, s80, v200
	v_cvt_pk_bf16_f32 v176, v176, s0
	s_nop 0
	v_addc_co_u32_e32 v211, vcc, 0, v201, vcc
	s_waitcnt vmcnt(14)
	v_mul_f32_e32 v195, 0x3a800000, v208
	global_store_short v[210:211], v176, off
	v_fma_f32 v176, -v127, v193, v19
	v_mul_f32_e32 v198, v195, v195
	v_fma_f32 v163, v176, v163, v123
	v_add_co_u32_e32 v200, vcc, s81, v200
	v_fma_f32 v198, v209, s40, -v198
	v_cvt_pk_bf16_f32 v163, v163, s0
	v_addc_co_u32_e32 v201, vcc, 0, v201, vcc
	v_add_f32_e32 v198, 0x3727c5ac, v198
	global_store_short v[200:201], v163, off
	v_mul_f32_e32 v200, 0x4f800000, v198
	v_cmp_gt_f32_e32 vcc, s73, v198
	v_lshlrev_b32_e32 v163, s45, v162
	v_and_b32_e32 v163, 0x1ffe, v163
	v_cndmask_b32_e32 v198, v198, v200, vcc
	v_sqrt_f32_e32 v200, v198
	v_lshrrev_b32_e32 v162, s2, v162
	v_or_b32_e32 v176, v163, v162
	v_lshlrev_b32_e32 v193, 1, v176
	v_bitop3_b32 v162, v163, s72, v162 bitop3:0xc8
	v_lshrrev_b32_e32 v163, 1, v176
	v_add_u32_e32 v176, -1, v200
	v_fma_f32 v201, -v176, v200, v198
	v_cmp_ge_f32_e64 s[0:1], 0, v201
	v_add_u32_e32 v201, 1, v200
	v_and_b32_e32 v193, 8, v193
	v_cndmask_b32_e64 v176, v200, v176, s[0:1]
	v_fma_f32 v200, -v201, v200, v198
	v_cmp_lt_f32_e64 s[0:1], 0, v200
	v_and_b32_e32 v163, 4, v163
	v_or3_b32 v162, v193, v162, v163
	v_cndmask_b32_e64 v176, v176, v201, s[0:1]
	v_mul_f32_e32 v200, 0x37800000, v176
	v_cndmask_b32_e32 v176, v176, v200, vcc
	v_cmp_class_f32_e32 vcc, v198, v205
	s_nop 1
	v_cndmask_b32_e32 v198, v176, v198, vcc
	v_div_scale_f32 v200, s[0:1], v198, v198, 1.0
	v_rcp_f32_e32 v201, v200
	v_lshlrev_b32_e32 v176, 1, v162
	v_lshl_add_u64 v[160:161], v[160:161], 0, v[176:177]
	v_fma_f32 v162, -v200, v201, 1.0
	v_fmac_f32_e32 v201, v162, v201
	v_div_scale_f32 v162, vcc, 1.0, v198, 1.0
	v_mul_f32_e32 v163, v162, v201
	v_fma_f32 v176, -v200, v163, v162
	v_fmac_f32_e32 v163, v176, v201
	v_fma_f32 v162, -v200, v163, v162
	v_div_fmas_f32 v162, v162, v201, v163
	v_div_fixup_f32 v176, v162, v198, 1.0
	v_fma_f32 v162, -v104, v195, v12
	v_fma_f32 v162, v162, v176, v108
	v_cvt_pk_bf16_f32 v162, v162, s0
	global_store_short v[160:161], v162, off
	v_fma_f32 v162, -v105, v195, v13
	v_fma_f32 v162, v162, v176, v109
	v_cvt_pk_bf16_f32 v193, v162, s0
	v_add_co_u32_e32 v162, vcc, s61, v160
	s_nop 1
	v_addc_co_u32_e32 v163, vcc, 0, v161, vcc
	global_store_short v[162:163], v193, off
	v_fma_f32 v162, -v106, v195, v14
	v_fma_f32 v162, v162, v176, v110
	v_cvt_pk_bf16_f32 v193, v162, s0
	v_add_co_u32_e32 v162, vcc, s67, v160
	s_nop 1
	v_addc_co_u32_e32 v163, vcc, 0, v161, vcc
	global_store_short v[162:163], v193, off
	v_fma_f32 v162, -v107, v195, v15
	v_fma_f32 v162, v162, v176, v111
	v_cvt_pk_bf16_f32 v193, v162, s0
	v_add_co_u32_e32 v162, vcc, s71, v160
	s_nop 1
	v_addc_co_u32_e32 v163, vcc, 0, v161, vcc
	global_store_short v[162:163], v193, off
	v_fma_f32 v162, -v96, v195, v8
	v_fma_f32 v162, v162, v176, v100
	v_cvt_pk_bf16_f32 v193, v162, s0
	v_add_co_u32_e32 v162, vcc, s59, v160
	s_nop 1
	v_addc_co_u32_e32 v163, vcc, 0, v161, vcc
	global_store_short v[162:163], v193, off
	v_fma_f32 v162, -v97, v195, v9
	v_fma_f32 v162, v162, v176, v101
	v_cvt_pk_bf16_f32 v193, v162, s0
	v_add_co_u32_e32 v162, vcc, s60, v160
	s_nop 1
	v_addc_co_u32_e32 v163, vcc, 0, v161, vcc
	global_store_short v[162:163], v193, off
	v_fma_f32 v162, -v98, v195, v10
	v_fma_f32 v162, v162, v176, v102
	v_cvt_pk_bf16_f32 v193, v162, s0
	v_add_co_u32_e32 v162, vcc, s66, v160
	s_nop 1
	v_addc_co_u32_e32 v163, vcc, 0, v161, vcc
	global_store_short v[162:163], v193, off
	v_fma_f32 v162, -v99, v195, v11
	v_fma_f32 v162, v162, v176, v103
	v_cvt_pk_bf16_f32 v193, v162, s0
	v_add_co_u32_e32 v162, vcc, s68, v160
	s_nop 1
	v_addc_co_u32_e32 v163, vcc, 0, v161, vcc
	global_store_short v[162:163], v193, off
	v_fma_f32 v162, -v112, v195, v4
	v_fma_f32 v162, v162, v176, v116
	v_cvt_pk_bf16_f32 v193, v162, s0
	v_add_co_u32_e32 v162, vcc, s74, v160
	s_nop 1
	v_addc_co_u32_e32 v163, vcc, 0, v161, vcc
	global_store_short v[162:163], v193, off
	v_fma_f32 v162, -v113, v195, v5
	v_fma_f32 v162, v162, v176, v117
	v_cvt_pk_bf16_f32 v193, v162, s0
	v_add_co_u32_e32 v162, vcc, s75, v160
	s_nop 1
	v_addc_co_u32_e32 v163, vcc, 0, v161, vcc
	global_store_short v[162:163], v193, off
	v_fma_f32 v162, -v114, v195, v6
	v_fma_f32 v162, v162, v176, v118
	v_cvt_pk_bf16_f32 v193, v162, s0
	v_add_co_u32_e32 v162, vcc, s76, v160
	s_nop 1
	v_addc_co_u32_e32 v163, vcc, 0, v161, vcc
	global_store_short v[162:163], v193, off
	v_fma_f32 v162, -v115, v195, v7
	v_fma_f32 v162, v162, v176, v119
	v_cvt_pk_bf16_f32 v193, v162, s0
	v_add_co_u32_e32 v162, vcc, s77, v160
	s_nop 1
	v_addc_co_u32_e32 v163, vcc, 0, v161, vcc
	global_store_short v[162:163], v193, off
	v_fma_f32 v162, -v124, v195, v0
	v_fma_f32 v162, v162, v176, v120
	v_cvt_pk_bf16_f32 v193, v162, s0
	v_add_co_u32_e32 v162, vcc, s78, v160
	s_nop 1
	v_addc_co_u32_e32 v163, vcc, 0, v161, vcc
	global_store_short v[162:163], v193, off
	v_fma_f32 v162, -v125, v195, v1
	v_fma_f32 v162, v162, v176, v121
	v_cvt_pk_bf16_f32 v193, v162, s0
	v_add_co_u32_e32 v162, vcc, s79, v160
	s_nop 1
	v_addc_co_u32_e32 v163, vcc, 0, v161, vcc
	global_store_short v[162:163], v193, off
	v_fma_f32 v162, -v126, v195, v2
	v_fma_f32 v162, v162, v176, v122
	v_cvt_pk_bf16_f32 v193, v162, s0
	v_add_co_u32_e32 v162, vcc, 0x98000, v160
	s_nop 1
	v_addc_co_u32_e32 v163, vcc, 0, v161, vcc
	global_store_short v[162:163], v193, off
	v_fma_f32 v162, -v127, v195, v3
	v_fma_f32 v162, v162, v176, v123
	v_add_co_u32_e32 v160, vcc, 0x9c000, v160
	v_cvt_pk_bf16_f32 v162, v162, s0
	s_nop 0
	v_addc_co_u32_e32 v161, vcc, 0, v161, vcc
	s_mov_b64 s[0:1], 0
	global_store_short v[160:161], v162, off
